# gla_a K/V loads and gla_c q/k/v + og-gate loads hoisted to the unit top into spare VGPRs (consumed via v_mov after the barrier)
# speedup vs baseline: 1.0191x; 1.0074x over previous
.LBB0_651:
	s_lshl_b32 s0, s28, 6
	s_add_i32 s43, s13, s0
	v_add_u32_e32 v6, s43, v128
	v_mov_b64_e32 v[0:1], s[20:21]
	v_mad_i64_i32 v[2:3], s[0:1], v6, s37, v[0:1]
	v_lshl_add_u64 v[2:3], v[2:3], 0, v[30:31]
	v_add_u32_e32 v4, 16, v6
	v_add_co_u32_e32 v2, vcc, 0x1000, v2
	v_mad_i64_i32 v[4:5], s[0:1], v4, s37, v[0:1]
	s_nop 0
	v_addc_co_u32_e32 v3, vcc, 0, v3, vcc
	v_lshl_add_u64 v[4:5], v[4:5], 0, v[30:31]
	v_add_co_u32_e32 v4, vcc, 0x1000, v4
	s_and_b32 s44, s12, 3
	s_nop 0
	v_addc_co_u32_e32 v5, vcc, 0, v5, vcc
	global_load_dwordx4 v[16:19], v[2:3], off offset:1344
	global_load_dwordx4 v[12:15], v[4:5], off offset:1344
	v_add_u32_e32 v2, 32, v6
	v_mad_i64_i32 v[2:3], s[0:1], v2, s37, v[0:1]
	v_lshl_add_u64 v[2:3], v[2:3], 0, v[30:31]
	v_add_u32_e32 v4, 48, v6
	v_add_co_u32_e32 v2, vcc, 0x1000, v2
	v_mad_i64_i32 v[0:1], s[0:1], v4, s37, v[0:1]
	s_nop 0
	v_addc_co_u32_e32 v3, vcc, 0, v3, vcc
	v_lshl_add_u64 v[0:1], v[0:1], 0, v[30:31]
	v_add_co_u32_e32 v0, vcc, 0x1000, v0
	s_lshl_b32 s22, s44, 9
	s_nop 0
	v_addc_co_u32_e32 v1, vcc, 0, v1, vcc
	global_load_dwordx4 v[8:11], v[2:3], off offset:1344
	s_nop 0
	global_load_dwordx4 v[0:3], v[0:1], off offset:1344
	v_lshl_add_u64 v[24:25], v[32:33], 0, s[22:23]
	v_mov_b32_e32 v4, 0
	v_lshlrev_b32_e32 v26, 2, v34
	v_mov_b32_e32 v20, 0
	s_waitcnt lgkmcnt(0)
	v_mov_b32_e32 v21, 0
	v_mov_b32_e32 v22, 0
	v_mov_b32_e32 v23, 0
	s_lshl_b32 s98, s44, 7
	s_or_b32 s98, s98, s34
	v_or_b32_e32 v208, s98, v34
	v_mov_b32_e32 v209, v31
	v_lshl_add_u64 v[208:209], v[208:209], 2, s[90:91]
	global_load_dword v210, v[208:209], off
	global_load_dword v211, v[208:209], off offset:64
	s_and_saveexec_b64 s[0:1], s[2:3]
	v_mov_b32_e32 v27, v31
	v_lshl_add_u64 v[6:7], v[24:25], 0, v[26:27]
	v_add_co_u32_e32 v20, vcc, 0x1000, v6
	s_nop 1
	v_addc_co_u32_e32 v21, vcc, 0, v7, vcc
	v_add_co_u32_e32 v22, vcc, 0x2000, v6
	s_nop 1
	v_addc_co_u32_e32 v23, vcc, 0, v7, vcc
	v_add_co_u32_e32 v28, vcc, 0x3000, v6
	s_nop 1
	v_addc_co_u32_e32 v29, vcc, 0, v7, vcc
	global_load_dword v200, v[6:7], off offset:64
	global_load_dword v201, v[6:7], off offset:2112
	global_load_dword v202, v[20:21], off offset:64
	global_load_dword v203, v[20:21], off offset:2112
	global_load_dword v204, v[22:23], off offset:64
	global_load_dword v205, v[22:23], off offset:2112
	global_load_dword v206, v[28:29], off offset:64
	global_load_dword v207, v[28:29], off offset:2112
	global_load_dword v5, v[6:7], off
	s_nop 0
	global_load_dword v6, v[6:7], off offset:2048
	s_nop 0
	global_load_dword v7, v[20:21], off
	s_nop 0
	global_load_dword v21, v[20:21], off offset:2048
	s_nop 0
	global_load_dword v27, v[22:23], off
	s_nop 0
	global_load_dword v22, v[22:23], off offset:2048
	s_nop 0
	global_load_dword v23, v[28:29], off
	s_nop 0
	global_load_dword v28, v[28:29], off offset:2048
	s_or_b64 exec, exec, s[0:1]
	v_add_u32_e32 v230, s43, v144
	v_mov_b64_e32 v[228:229], s[20:21]
	v_mad_i64_i32 v[228:229], vcc, v230, s37, v[228:229]
	s_lshl_b32 s100, s44, 8
	s_mov_b32 s101, 0
	v_lshl_add_u64 v[228:229], v[228:229], 0, s[100:101]
	v_mov_b32_e32 v230, v40
	v_mov_b32_e32 v231, v31
	v_lshl_add_u64 v[228:229], v[228:229], 0, v[230:231]
	global_load_dwordx4 v[212:215], v[228:229], off offset:2368
	global_load_dwordx4 v[216:219], v[228:229], off offset:3392
	global_load_dwordx4 v[220:223], v[228:229], off offset:2496
	global_load_dwordx4 v[224:227], v[228:229], off offset:3520
	s_waitcnt vmcnt(4)
	s_and_saveexec_b64 s[0:1], s[2:3]
	v_cvt_pk_bf16_f32 v20, v5, v6
	v_cvt_pk_bf16_f32 v21, v7, v21
	v_cvt_pk_bf16_f32 v22, v27, v22
	v_cvt_pk_bf16_f32 v23, v23, v28
.LBB0_653:
	s_or_b64 exec, exec, s[0:1]
	s_lshl_b32 s22, s44, 7
	s_or_b32 s45, s22, s34
	v_mov_b32_e32 v5, v210
	v_mfma_f32_16x16x32_bf16 v[42:45], v[16:19], v[20:23], 0
	v_add_u32_e32 v28, 0x400, v126
	v_mfma_f32_16x16x32_bf16 v[46:49], v[12:15], v[20:23], 0
	s_nop 5
	v_add_f32_e32 v6, v5, v42
	v_add_f32_e32 v7, v5, v43
	v_min_f32_e32 v43, 0, v6
	v_mul_f32_e64 v6, |v6|, s38
	v_add_f32_e32 v27, v5, v44
	v_min_f32_e32 v44, 0, v7
	v_mul_f32_e64 v7, |v7|, s38
	v_exp_f32_e32 v6, v6
	v_add_f32_e32 v29, v5, v45
	v_min_f32_e32 v45, 0, v27
	v_mul_f32_e64 v27, |v27|, s38
	v_exp_f32_e32 v7, v7
	v_add_f32_e32 v41, v5, v46
	v_min_f32_e32 v46, 0, v29
	v_mul_f32_e64 v29, |v29|, s38
	v_exp_f32_e32 v27, v27
	v_exp_f32_e32 v29, v29
	v_add_f32_e32 v6, 1.0, v6
	v_add_f32_e32 v7, 1.0, v7
	v_add_f32_e32 v42, v5, v47
	v_min_f32_e32 v47, 0, v41
	v_mul_f32_e64 v41, |v41|, s38
	v_add_f32_e32 v27, 1.0, v27
	v_exp_f32_e32 v41, v41
	v_add_f32_e32 v29, 1.0, v29
	v_log_f32_e32 v6, v6
	v_log_f32_e32 v7, v7
	v_log_f32_e32 v27, v27
	v_add_f32_e32 v41, 1.0, v41
	v_log_f32_e32 v29, v29
	v_cmp_gt_f32_e64 s[16:17], s39, v41
	v_cndmask_b32_e64 v55, 0, 32, s[16:17]
	v_ldexp_f32 v41, v41, v55
	v_log_f32_e32 v41, v41
	v_mul_f32_e64 v50, |v42|, s38
	v_exp_f32_e32 v50, v50
	v_mul_f32_e32 v60, 0x3f317217, v41
	v_fma_f32 v60, v41, s40, -v60
	v_fma_f32 v6, -v6, s40, v43
	v_fma_f32 v7, -v7, s40, v44
	v_fmac_f32_e32 v60, 0x3377d1cf, v41
	v_fma_f32 v27, -v27, s40, v45
	v_fma_f32 v29, -v29, s40, v46
	v_mul_f32_e32 v6, 0x3d800000, v6
	v_mul_f32_e32 v7, 0x3d800000, v7
	v_fmac_f32_e32 v60, 0x3f317217, v41
	v_cmp_lt_f32_e64 vcc, |v41|, s41
	v_mul_f32_e32 v27, 0x3d800000, v27
	v_mul_f32_e32 v29, 0x3d800000, v29
	ds_write2_b32 v126, v6, v7 offset1:129
	ds_write2_b32 v28, v27, v29 offset0:2 offset1:131
	v_add_f32_e32 v7, 1.0, v50
	v_cndmask_b32_e32 v41, v41, v60, vcc
	v_cndmask_b32_e64 v55, 0, v125, s[16:17]
	v_sub_f32_e32 v6, v41, v55
	v_log_f32_e32 v7, v7
	v_add_f32_e32 v41, v5, v48
	v_min_f32_e32 v27, 0, v42
	v_mul_f32_e64 v42, |v41|, s38
	v_exp_f32_e32 v42, v42
	v_sub_f32_e32 v6, v47, v6
	v_mul_f32_e32 v6, 0x3d800000, v6
	v_fma_f32 v7, -v7, s40, v27
	v_add_f32_e32 v27, 1.0, v42
	v_cmp_gt_f32_e32 vcc, s39, v27
	v_mul_f32_e32 v7, 0x3d800000, v7
	s_nop 0
	v_cndmask_b32_e64 v29, 0, 32, vcc
	v_ldexp_f32 v27, v27, v29
	v_log_f32_e32 v27, v27
	v_add_u32_e32 v29, 0x2000, v126
	ds_write2_b32 v29, v6, v7 offset0:16 offset1:145
	v_min_f32_e32 v6, 0, v41
	v_add_f32_e32 v41, v5, v49
	v_mul_f32_e32 v7, 0x3f317217, v27
	v_mul_f32_e64 v42, |v41|, s38
	v_fma_f32 v7, v27, s40, -v7
	v_exp_f32_e32 v42, v42
	v_fmac_f32_e32 v7, 0x3377d1cf, v27
	v_fmac_f32_e32 v7, 0x3f317217, v27
	v_cmp_lt_f32_e64 s[0:1], |v27|, s41
	s_nop 1
	v_cndmask_b32_e64 v7, v27, v7, s[0:1]
	v_cndmask_b32_e32 v27, 0, v125, vcc
	v_sub_f32_e32 v7, v7, v27
	v_add_f32_e32 v27, 1.0, v42
	v_sub_f32_e32 v6, v6, v7
	v_min_f32_e32 v7, 0, v41
	v_log_f32_e32 v27, v27
	v_mfma_f32_16x16x32_bf16 v[42:45], v[8:11], v[20:23], 0
	v_mul_f32_e32 v6, 0x3d800000, v6
	s_nop 3
	s_nop 2
	v_add_f32_e32 v42, v5, v42
	v_mul_f32_e64 v46, |v42|, s38
	v_exp_f32_e32 v46, v46
	v_mfma_f32_16x16x32_bf16 v[20:23], v[0:3], v[20:23], 0
	s_nop 0
	v_fma_f32 v7, -v27, s40, v7
	v_add_f32_e32 v27, 1.0, v46
	v_cmp_gt_f32_e32 vcc, s39, v27
	v_mul_f32_e32 v7, 0x3d800000, v7
	s_nop 2
	v_add_f32_e32 v21, v5, v21
	v_cndmask_b32_e64 v41, 0, 32, vcc
	v_ldexp_f32 v27, v27, v41
	v_log_f32_e32 v27, v27
	v_add_u32_e32 v41, 0x2400, v126
	ds_write2_b32 v41, v6, v7 offset0:18 offset1:147
	v_min_f32_e32 v6, 0, v42
	v_add_f32_e32 v42, v5, v43
	v_mul_f32_e32 v7, 0x3f317217, v27
	v_mul_f32_e64 v43, |v42|, s38
	v_fma_f32 v7, v27, s40, -v7
	v_exp_f32_e32 v43, v43
	v_fmac_f32_e32 v7, 0x3377d1cf, v27
	v_fmac_f32_e32 v7, 0x3f317217, v27
	v_cmp_lt_f32_e64 s[0:1], |v27|, s41
	v_add_f32_e32 v22, v5, v22
	s_nop 0
	v_cndmask_b32_e64 v7, v27, v7, s[0:1]
	v_cndmask_b32_e32 v27, 0, v125, vcc
	v_sub_f32_e32 v7, v7, v27
	v_add_f32_e32 v27, 1.0, v43
	v_sub_f32_e32 v6, v6, v7
	v_min_f32_e32 v7, 0, v42
	v_log_f32_e32 v27, v27
	v_add_f32_e32 v43, v5, v44
	v_mul_f32_e64 v44, |v43|, s38
	v_exp_f32_e32 v44, v44
	v_mul_f32_e32 v6, 0x3d800000, v6
	s_nop 0
	v_fma_f32 v7, -v27, s40, v7
	v_add_f32_e32 v27, 1.0, v44
	v_cmp_gt_f32_e32 vcc, s39, v27
	v_mul_f32_e32 v7, 0x3d800000, v7
	s_nop 0
	v_cndmask_b32_e64 v42, 0, 32, vcc
	v_ldexp_f32 v27, v27, v42
	v_log_f32_e32 v27, v27
	v_add_u32_e32 v42, 0x4000, v126
	ds_write2_b32 v42, v6, v7 offset0:32 offset1:161
	v_min_f32_e32 v6, 0, v43
	v_add_f32_e32 v43, v5, v45
	v_mul_f32_e32 v7, 0x3f317217, v27
	v_mul_f32_e64 v44, |v43|, s38
	v_fma_f32 v7, v27, s40, -v7
	v_exp_f32_e32 v44, v44
	v_fmac_f32_e32 v7, 0x3377d1cf, v27
	v_fmac_f32_e32 v7, 0x3f317217, v27
	v_cmp_lt_f32_e64 s[0:1], |v27|, s41
	s_nop 1
	v_cndmask_b32_e64 v7, v27, v7, s[0:1]
	v_cndmask_b32_e32 v27, 0, v125, vcc
	v_sub_f32_e32 v7, v7, v27
	v_add_f32_e32 v27, 1.0, v44
	v_sub_f32_e32 v6, v6, v7
	v_min_f32_e32 v7, 0, v43
	v_log_f32_e32 v27, v27
	v_add_f32_e32 v44, v5, v20
	v_mul_f32_e64 v20, |v44|, s38
	v_exp_f32_e32 v20, v20
	s_nop 0
	v_add_f32_e32 v20, 1.0, v20
	v_mul_f32_e32 v6, 0x3d800000, v6
	v_cmp_gt_f32_e32 vcc, s39, v20
	v_fma_f32 v7, -v27, s40, v7
	v_mul_f32_e32 v7, 0x3d800000, v7
	v_cndmask_b32_e64 v27, 0, 32, vcc
	v_ldexp_f32 v20, v20, v27
	v_log_f32_e32 v27, v20
	v_add_u32_e32 v20, 0x4400, v126
	ds_write2_b32 v20, v6, v7 offset0:34 offset1:163
	v_mul_f32_e64 v43, |v21|, s38
	v_mul_f32_e32 v7, 0x3f317217, v27
	v_fma_f32 v7, v27, s40, -v7
	v_exp_f32_e32 v43, v43
	v_fmac_f32_e32 v7, 0x3377d1cf, v27
	v_fmac_f32_e32 v7, 0x3f317217, v27
	v_cmp_lt_f32_e64 s[0:1], |v27|, s41
	v_min_f32_e32 v6, 0, v44
	v_add_f32_e32 v5, v5, v23
	v_cndmask_b32_e64 v7, v27, v7, s[0:1]
	v_cndmask_b32_e32 v27, 0, v125, vcc
	v_sub_f32_e32 v7, v7, v27
	v_add_f32_e32 v27, 1.0, v43
	v_sub_f32_e32 v6, v6, v7
	v_min_f32_e32 v7, 0, v21
	v_log_f32_e32 v27, v27
	v_mul_f32_e64 v43, |v22|, s38
	v_exp_f32_e32 v43, v43
	v_mul_f32_e32 v6, 0x3d800000, v6
	s_nop 1
	v_fma_f32 v7, -v27, s40, v7
	v_add_f32_e32 v21, 1.0, v43
	v_mul_f32_e32 v7, 0x3d800000, v7
	s_nop 0
	v_log_f32_e32 v27, v21
	v_add_u32_e32 v21, 0x6000, v126
	ds_write2_b32 v21, v6, v7 offset0:48 offset1:177
	v_min_f32_e32 v6, 0, v22
	v_mul_f32_e64 v22, |v5|, s38
	v_exp_f32_e32 v22, v22
	s_nop 0
	v_add_f32_e32 v22, 1.0, v22
	v_fma_f32 v6, -v27, s40, v6
	v_log_f32_e32 v22, v22
	v_min_f32_e32 v5, 0, v5
	v_mul_f32_e32 v6, 0x3d800000, v6
	s_nop 1
	v_fma_f32 v5, -v22, s40, v5
	v_mul_f32_e32 v5, 0x3d800000, v5
	v_add_u32_e32 v22, 0x6400, v126
	ds_write2_b32 v22, v6, v5 offset0:50 offset1:179
	v_mov_b32_e32 v5, 0
	v_mov_b32_e32 v6, 0
	v_mov_b32_e32 v7, 0
	s_and_saveexec_b64 s[0:1], s[2:3]
	s_cbranch_execz .LBB0_655
	v_cvt_pk_bf16_f32 v4, v200, v201
	v_cvt_pk_bf16_f32 v5, v202, v203
	v_cvt_pk_bf16_f32 v6, v204, v205
	v_cvt_pk_bf16_f32 v7, v206, v207
.LBB0_655:
	s_or_b64 exec, exec, s[0:1]
	v_add_u32_e32 v24, s45, v34
	v_mov_b32_e32 v25, v31
	v_lshl_add_u64 v[24:25], v[24:25], 2, s[90:91]
	v_mov_b32_e32 v23, v211
	v_mfma_f32_16x16x32_bf16 v[16:19], v[16:19], v[4:7], 0
	v_add_u32_e32 v129, 0x800, v127
	v_add_u32_e32 v130, 0xc00, v127
	v_add_u32_e32 v132, 0x1000, v127
	v_mfma_f32_16x16x32_bf16 v[12:15], v[12:15], v[4:7], 0
	v_add_u32_e32 v135, 0x1400, v127
	v_add_u32_e32 v138, 0x1800, v127
	v_add_u32_e32 v133, 0x1c00, v127
	v_mfma_f32_16x16x32_bf16 v[8:11], v[8:11], v[4:7], 0
	v_add_u32_e32 v136, 0x2000, v127
	v_add_u32_e32 v139, 0x2400, v127
	v_add_u32_e32 v141, 0x2800, v127
	v_mfma_f32_16x16x32_bf16 v[0:3], v[0:3], v[4:7], 0
	v_add_u32_e32 v142, 0x2c00, v127
	v_add_u32_e32 v140, 0x3000, v127
	v_add_u32_e32 v137, 0x3400, v127
	v_add_u32_e32 v134, 0x3800, v127
	v_add_u32_e32 v131, 0x3c00, v127
	s_add_i32 s98, s30, s72
	s_cmpk_lt_i32 s98, 0x880
	s_cbranch_scc0 .Lpf_a_skip
	s_cmpk_gt_i32 s98, 0x7ff
	s_cbranch_scc1 .Lpf_a_ctx
	s_lshr_b32 s99, s98, 8
	s_bfe_u32 s100, s98, 0x20006
	s_and_b32 s101, s98, 63
	s_lshl_b32 s99, s99, 12
	s_branch .Lpf_a_go

.LBB0_659:
	s_or_b64 exec, exec, s[0:1]
	s_waitcnt lgkmcnt(1)
	v_lshl_add_u32 v44, v146, 2, 0
	v_add_u32_e32 v44, 0x10600, v44
	ds_write_b32 v44, v143
	s_waitcnt lgkmcnt(0)
	s_barrier
	ds_read_b32 v44, v74 offset:1024
	s_waitcnt lgkmcnt(0)
	v_cndmask_b32_e64 v45, 0, v44, s[8:9]
	v_cndmask_b32_e64 v46, 0, v44, s[10:11]
	v_cndmask_b32_e64 v45, v46, v45, s[4:5]
	v_add_f32_e32 v2, v2, v45
	v_add_f32_e32 v3, v3, v45
	v_add_f32_e32 v4, v4, v45
	v_add_f32_e32 v5, v5, v45
	v_add_f32_e32 v6, v6, v45
	v_add_f32_e32 v7, v7, v45
	v_add_f32_e32 v8, v8, v45
	v_add_f32_e32 v9, v9, v45
	v_add_f32_e32 v10, v10, v45
	v_add_f32_e32 v11, v11, v45
	v_add_f32_e32 v12, v12, v45
	v_add_f32_e32 v13, v13, v45
	ds_write2_b32 v41, v2, v3 offset0:2 offset1:131
	ds_write2_b32 v129, v4, v5 offset0:4 offset1:133
	ds_write2_b32 v130, v6, v7 offset0:6 offset1:135
	ds_write2_b32 v132, v8, v9 offset0:8 offset1:137
	ds_write2_b32 v135, v10, v11 offset0:10 offset1:139
	ds_write2_b32 v138, v12, v13 offset0:12 offset1:141
	v_add_f32_e32 v2, v0, v45
	v_add_f32_e32 v1, v1, v45
	v_add_f32_e32 v14, v14, v45
	v_add_f32_e32 v15, v15, v45
	v_add_f32_e32 v16, v16, v45
	v_add_f32_e32 v17, v17, v45
	v_add_f32_e32 v18, v18, v45
	v_add_f32_e32 v19, v19, v45
	v_add_f32_e32 v20, v20, v45
	v_add_f32_e32 v21, v21, v45
	v_add_f32_e32 v22, v22, v45
	ds_write2_b32 v127, v2, v1 offset1:129
	ds_write2_b32 v133, v14, v15 offset0:14 offset1:143
	ds_write2_b32 v136, v16, v17 offset0:16 offset1:145
	ds_write2_b32 v139, v18, v19 offset0:18 offset1:147
	ds_write2_b32 v141, v20, v21 offset0:20 offset1:149
	v_add_f32_e32 v1, v23, v45
	ds_write2_b32 v142, v22, v1 offset0:22 offset1:151
	v_add_f32_e32 v1, v24, v45
	v_add_f32_e32 v2, v25, v45
	ds_write2_b32 v140, v1, v2 offset0:24 offset1:153
	v_add_f32_e32 v1, v26, v45
	v_add_f32_e32 v2, v27, v45
	ds_write2_b32 v137, v1, v2 offset0:26 offset1:155
	v_add_f32_e32 v1, v28, v45
	v_add_f32_e32 v2, v29, v45
	ds_write2_b32 v134, v1, v2 offset0:28 offset1:157
	v_add_f32_e32 v1, v42, v45
	v_add_f32_e32 v2, v43, v45
	ds_write2_b32 v131, v1, v2 offset0:30 offset1:159
	s_and_saveexec_b64 s[0:1], s[10:11]
	v_cndmask_b32_e64 v0, v0, v44, s[4:5]
	v_cndmask_b32_e64 v1, v44, v43, s[4:5]
	v_add_f32_e32 v0, v0, v1
	ds_write_b32 v75, v0
	s_or_b64 exec, exec, s[0:1]
	s_lshl_b32 s0, s29, 3
	s_lshl_b32 s1, s44, 1
	s_or_b32 s12, s0, s1
	s_waitcnt vmcnt(0) lgkmcnt(0)
	s_barrier
	s_and_saveexec_b64 s[0:1], s[10:11]
	s_cbranch_execz .LBB0_663
	ds_read_b32 v0, v75
	s_add_i32 s13, s28, 4
	s_and_b64 s[14:15], exec, s[26:27]
	s_cselect_b32 s13, s28, s13
	v_or_b32_e32 v2, s12, v35
	s_waitcnt lgkmcnt(0)
	v_mul_f32_e32 v0, 0x3fb8aa3b, v0
	v_exp_f32_e32 v3, v0
	v_mov_b32_e32 v0, s13
	v_mov_b32_e32 v1, v31
	v_mad_i64_i32 v[0:1], s[14:15], v2, s42, v[0:1]
	v_lshlrev_b64 v[0:1], 9, v[0:1]
	v_lshl_add_u64 v[0:1], v[36:37], 0, v[0:1]
	global_store_dword v[0:1], v3, off
.LBB0_663:
	s_or_b64 exec, exec, s[0:1]
	v_add_u32_e32 v2, s43, v144
	v_mov_b64_e32 v[0:1], s[20:21]
	v_mad_i64_i32 v[0:1], s[0:1], v2, s37, v[0:1]
	s_lshl_b32 s22, s22, 1
	v_lshl_add_u64 v[0:1], v[0:1], 0, s[22:23]
	v_mov_b32_e32 v41, v31
	v_lshl_add_u64 v[0:1], v[0:1], 0, v[40:41]
	v_mov_b32_e32 v8, v212
	v_mov_b32_e32 v9, v213
	v_mov_b32_e32 v10, v214
	v_mov_b32_e32 v11, v215
	v_mov_b32_e32 v12, v216
	v_mov_b32_e32 v13, v217
	v_mov_b32_e32 v14, v218
	v_mov_b32_e32 v15, v219
	v_add_u32_e32 v2, 0x8100, v77
	v_add_u32_e32 v3, 0x8108, v77
	v_add_u32_e32 v4, 0x8110, v77
	v_add_u32_e32 v5, 0x8200, v77
	ds_read_b128 v[16:19], v76
	ds_read2_b32 v[28:29], v77 offset1:1
	ds_read_b128 v[20:23], v78
	ds_read_b96 v[24:26], v87
	ds_read_b96 v[42:44], v88
	ds_read2_b32 v[46:47], v77 offset0:2 offset1:3
	ds_read2_b32 v[48:49], v77 offset0:4 offset1:5
	ds_read2_b32 v[50:51], v77 offset0:64 offset1:65
	ds_read2_b32 v[52:53], v77 offset0:66 offset1:67
	ds_read2_b32 v[54:55], v2 offset1:1
	ds_read2_b32 v[56:57], v3 offset1:1
	ds_read2_b32 v[58:59], v4 offset1:1
	ds_read2_b32 v[60:61], v5 offset1:1
	v_mov_b32_e32 v4, v220
	v_mov_b32_e32 v5, v221
	v_mov_b32_e32 v6, v222
	v_mov_b32_e32 v7, v223
	v_mov_b32_e32 v0, v224
	v_mov_b32_e32 v1, v225
	v_mov_b32_e32 v2, v226
	v_mov_b32_e32 v3, v227
	s_waitcnt lgkmcnt(7)
	v_sub_f32_e32 v19, v19, v47
	v_sub_f32_e32 v16, v16, v28
	v_sub_f32_e32 v17, v17, v29
	s_waitcnt lgkmcnt(3)
	v_sub_f32_e32 v21, v21, v55
	s_waitcnt lgkmcnt(2)
	v_sub_f32_e32 v23, v23, v57
	v_sub_f32_e32 v18, v18, v46
	v_mul_f32_e32 v16, 0x3fb8aa3b, v16
	v_sub_f32_e32 v20, v20, v54
	v_mul_f32_e32 v17, 0x3fb8aa3b, v17
	v_sub_f32_e32 v22, v22, v56
	v_mul_f32_e32 v19, 0x3fb8aa3b, v19
	v_mul_f32_e32 v21, 0x3fb8aa3b, v21
	v_mul_f32_e32 v23, 0x3fb8aa3b, v23
	v_mul_f32_e32 v18, 0x3fb8aa3b, v18
	v_exp_f32_e32 v16, v16
	v_mul_f32_e32 v20, 0x3fb8aa3b, v20
	v_exp_f32_e32 v17, v17
	v_mul_f32_e32 v22, 0x3fb8aa3b, v22
	v_exp_f32_e32 v19, v19
	v_exp_f32_e32 v21, v21
	v_exp_f32_e32 v23, v23
	v_exp_f32_e32 v18, v18
	v_exp_f32_e32 v20, v20
	v_exp_f32_e32 v22, v22
	v_sub_f32_e32 v24, v24, v48
	v_mul_f32_e32 v24, 0x3fb8aa3b, v24
	s_mov_b32 s29, s23
	v_lshlrev_b32_e32 v27, 16, v8
	v_and_b32_e32 v8, 0xffff0000, v8
	v_lshlrev_b32_e32 v28, 16, v9
	v_and_b32_e32 v9, 0xffff0000, v9
	v_mul_f32_e32 v16, v16, v27
	v_mul_f32_e32 v17, v17, v8
	v_mul_f32_e32 v8, v21, v8
	v_mul_f32_e32 v19, v19, v9
	v_mul_f32_e32 v9, v23, v9
	v_mul_f32_e32 v20, v20, v27
	v_mul_f32_e32 v18, v18, v28
	v_mul_f32_e32 v21, v22, v28
	v_cvt_pk_bf16_f32 v16, v16, s0
	v_cvt_pk_bf16_f32 v8, v8, s0
	v_cvt_pk_bf16_f32 v9, v9, s0
	v_cvt_pk_bf16_f32 v20, v20, s0
	v_cvt_pk_bf16_f32 v17, v17, s0
	v_cvt_pk_bf16_f32 v18, v18, s0
	v_cvt_pk_bf16_f32 v21, v21, s0
	v_cvt_pk_bf16_f32 v19, v19, s0
	ds_write_b16 v79, v16
	ds_write_b16 v121, v20
	ds_write_b16 v80, v12
	ds_write_b16 v81, v17
	ds_write_b16 v121, v8 offset:144
	ds_write_b16_d16_hi v82, v12
	ds_write_b16 v83, v18
	ds_write_b16 v121, v21 offset:288
	ds_write_b16 v84, v13
	ds_write_b16 v85, v19
	ds_write_b16 v121, v9 offset:432
	ds_write_b16_d16_hi v86, v13
	v_exp_f32_e32 v8, v24
	s_waitcnt lgkmcnt(13)
	v_sub_f32_e32 v9, v42, v58
	v_mul_f32_e32 v9, 0x3fb8aa3b, v9
	v_exp_f32_e32 v9, v9
	v_lshlrev_b32_e32 v29, 16, v10
	v_mul_f32_e32 v8, v8, v29
	v_cvt_pk_bf16_f32 v8, v8, s0
	ds_read_b32 v12, v95
	ds_read_b32 v13, v97
	ds_write_b16 v89, v8
	v_mul_f32_e32 v8, v9, v29
	v_cvt_pk_bf16_f32 v8, v8, s0
	v_sub_f32_e32 v9, v25, v49
	ds_write_b16 v121, v8 offset:576
	ds_write_b16 v90, v14
	v_and_b32_e32 v8, 0xffff0000, v10
	v_mul_f32_e32 v9, 0x3fb8aa3b, v9
	v_sub_f32_e32 v10, v43, v59
	v_exp_f32_e32 v9, v9
	v_mul_f32_e32 v10, 0x3fb8aa3b, v10
	v_exp_f32_e32 v10, v10
	v_lshlrev_b32_e32 v16, 16, v4
	v_mul_f32_e32 v9, v9, v8
	v_cvt_pk_bf16_f32 v9, v9, s0
	v_mul_f32_e32 v10, v10, v8
	v_add_u32_e32 v8, 24, v77
	ds_write_b16 v91, v9
	ds_read2st64_b32 v[8:9], v8 offset1:129
	v_cvt_pk_bf16_f32 v10, v10, s0
	ds_write_b16 v121, v10 offset:720
	ds_write_b16_d16_hi v92, v14
	v_lshlrev_b32_e32 v10, 16, v11
	v_and_b32_e32 v4, 0xffff0000, v4
	s_waitcnt lgkmcnt(2)
	v_sub_f32_e32 v8, v26, v8
	v_mul_f32_e32 v8, 0x3fb8aa3b, v8
	v_exp_f32_e32 v8, v8
	v_sub_f32_e32 v9, v44, v9
	v_mul_f32_e32 v9, 0x3fb8aa3b, v9
	v_exp_f32_e32 v9, v9
	v_mul_f32_e32 v8, v8, v10
	v_cvt_pk_bf16_f32 v8, v8, s0
	ds_write_b16 v93, v8
	v_mul_f32_e32 v10, v9, v10
	ds_read2st64_b32 v[8:9], v96 offset1:129
	v_cvt_pk_bf16_f32 v10, v10, s0
	ds_write_b16 v121, v10 offset:864
	ds_write_b16 v94, v15
	v_and_b32_e32 v10, 0xffff0000, v11
	v_lshlrev_b32_e32 v20, 16, v6
	s_waitcnt lgkmcnt(2)
	v_sub_f32_e32 v8, v12, v8
	v_mul_f32_e32 v8, 0x3fb8aa3b, v8
	v_exp_f32_e32 v8, v8
	v_sub_f32_e32 v9, v13, v9
	v_mul_f32_e32 v9, 0x3fb8aa3b, v9
	v_exp_f32_e32 v9, v9
	v_mul_f32_e32 v8, v8, v10
	v_cvt_pk_bf16_f32 v8, v8, s0
	ds_write_b16 v98, v8
	v_mul_f32_e32 v8, v9, v10
	v_cvt_pk_bf16_f32 v12, v8, s0
	ds_read_b128 v[8:11], v100
	ds_write_b16 v122, v12
	ds_write_b16_d16_hi v99, v15
	ds_read_b128 v[12:15], v101
	s_waitcnt lgkmcnt(3)
	v_sub_f32_e32 v8, v8, v50
	v_mul_f32_e32 v8, 0x3fb8aa3b, v8
	v_exp_f32_e32 v8, v8
	s_waitcnt lgkmcnt(0)
	v_sub_f32_e32 v12, v12, v60
	v_mul_f32_e32 v12, 0x3fb8aa3b, v12
	v_exp_f32_e32 v12, v12
	v_mul_f32_e32 v8, v8, v16
	v_cvt_pk_bf16_f32 v8, v8, s0
	ds_write_b16 v102, v8
	v_mul_f32_e32 v8, v12, v16
	v_cvt_pk_bf16_f32 v8, v8, s0
	ds_write_b16 v121, v8 offset:9216
	ds_write_b16 v103, v0
	v_sub_f32_e32 v8, v9, v51
	v_sub_f32_e32 v9, v13, v61
	v_mul_f32_e32 v8, 0x3fb8aa3b, v8
	v_mul_f32_e32 v9, 0x3fb8aa3b, v9
	v_exp_f32_e32 v8, v8
	v_exp_f32_e32 v9, v9
	v_add_u32_e32 v12, 0x8218, v77
	v_mul_f32_e32 v8, v8, v4
	v_mul_f32_e32 v4, v9, v4
	v_cvt_pk_bf16_f32 v8, v8, s0
	v_cvt_pk_bf16_f32 v4, v4, s0
	ds_write_b16 v104, v8
	ds_write_b16 v121, v4 offset:9360
	ds_write_b16_d16_hi v105, v0
	v_add_u32_e32 v8, 0x8208, v77
	ds_read2_b32 v[8:9], v8 offset1:1
	v_sub_f32_e32 v4, v10, v52
	v_mul_f32_e32 v4, 0x3fb8aa3b, v4
	v_exp_f32_e32 v4, v4
	v_lshlrev_b32_e32 v0, 16, v5
	s_waitcnt lgkmcnt(0)
	v_sub_f32_e32 v8, v14, v8
	v_mul_f32_e32 v8, 0x3fb8aa3b, v8
	v_exp_f32_e32 v8, v8
	v_mul_f32_e32 v4, v4, v0
	v_add_u32_e32 v10, 0x8210, v77
	v_cvt_pk_bf16_f32 v4, v4, s0
	v_mul_f32_e32 v0, v8, v0
	v_cvt_pk_bf16_f32 v0, v0, s0
	ds_read2_b32 v[16:17], v10 offset1:1
	ds_read2_b32 v[18:19], v12 offset1:1
	ds_write_b16 v106, v4
	ds_write_b16 v121, v0 offset:9504
	ds_write_b16 v107, v1
	v_and_b32_e32 v0, 0xffff0000, v5
	v_sub_f32_e32 v4, v11, v53
	v_sub_f32_e32 v5, v15, v9
	v_mul_f32_e32 v4, 0x3fb8aa3b, v4
	v_mul_f32_e32 v5, 0x3fb8aa3b, v5
	v_exp_f32_e32 v4, v4
	v_exp_f32_e32 v5, v5
	v_mul_f32_e32 v4, v4, v0
	v_mul_f32_e32 v0, v5, v0
	v_cvt_pk_bf16_f32 v4, v4, s0
	v_cvt_pk_bf16_f32 v0, v0, s0
	ds_write_b16 v108, v4
	ds_write_b16 v121, v0 offset:9648
	ds_read_b128 v[8:11], v110
	ds_read2_b32 v[4:5], v77 offset0:68 offset1:69
	ds_write_b16_d16_hi v109, v1
	ds_read_b128 v[12:15], v111
	ds_read2_b32 v[0:1], v77 offset0:70 offset1:71
	s_waitcnt lgkmcnt(3)
	v_sub_f32_e32 v4, v8, v4
	v_mul_f32_e32 v4, 0x3fb8aa3b, v4
	v_exp_f32_e32 v4, v4
	s_waitcnt lgkmcnt(1)
	v_sub_f32_e32 v8, v12, v16
	v_mul_f32_e32 v8, 0x3fb8aa3b, v8
	v_exp_f32_e32 v8, v8
	v_mul_f32_e32 v4, v4, v20
	v_cvt_pk_bf16_f32 v4, v4, s0
	ds_write_b16 v112, v4
	v_mul_f32_e32 v4, v8, v20
	v_cvt_pk_bf16_f32 v4, v4, s0
	ds_write_b16 v121, v4 offset:9792
	ds_write_b16 v113, v2
	v_and_b32_e32 v4, 0xffff0000, v6
	v_sub_f32_e32 v5, v9, v5
	v_sub_f32_e32 v6, v13, v17
	v_mul_f32_e32 v5, 0x3fb8aa3b, v5
	v_mul_f32_e32 v6, 0x3fb8aa3b, v6
	v_exp_f32_e32 v5, v5
	v_exp_f32_e32 v6, v6
	s_waitcnt lgkmcnt(3)
	v_sub_f32_e32 v0, v10, v0
	v_mul_f32_e32 v0, 0x3fb8aa3b, v0
	v_mul_f32_e32 v5, v5, v4
	v_mul_f32_e32 v4, v6, v4
	v_cvt_pk_bf16_f32 v5, v5, s0
	v_cvt_pk_bf16_f32 v4, v4, s0
	ds_write_b16 v114, v5
	ds_write_b16 v121, v4 offset:9936
	ds_write_b16_d16_hi v115, v2
	v_exp_f32_e32 v0, v0
	v_sub_f32_e32 v4, v14, v18
	v_mul_f32_e32 v4, 0x3fb8aa3b, v4
	v_exp_f32_e32 v4, v4
	v_lshlrev_b32_e32 v2, 16, v7
	v_mul_f32_e32 v0, v0, v2
	v_cvt_pk_bf16_f32 v0, v0, s0
	ds_write_b16 v116, v0
	v_mul_f32_e32 v0, v4, v2
	v_sub_f32_e32 v1, v11, v1
	v_sub_f32_e32 v2, v15, v19
	v_mul_f32_e32 v1, 0x3fb8aa3b, v1
	v_mul_f32_e32 v2, 0x3fb8aa3b, v2
	v_exp_f32_e32 v1, v1
	v_exp_f32_e32 v2, v2
	v_cvt_pk_bf16_f32 v0, v0, s0
	ds_write_b16 v121, v0 offset:10080
	ds_write_b16 v117, v3
	v_and_b32_e32 v0, 0xffff0000, v7
	v_mul_f32_e32 v1, v1, v0
	v_mul_f32_e32 v0, v2, v0
	v_cvt_pk_bf16_f32 v1, v1, s0
	v_cvt_pk_bf16_f32 v0, v0, s0
	s_add_i32 s0, s12, s31
	ds_write_b16 v118, v1
	ds_write_b16 v121, v0 offset:10224
	ds_write_b16_d16_hi v119, v3
	s_waitcnt lgkmcnt(0)
	s_barrier
	ds_read_b128 v[0:3], v123
	ds_read_b128 v[4:7], v123 offset:64
	ds_read_b128 v[8:11], v124
	ds_read_b128 v[12:15], v124 offset:64
	s_ashr_i32 s1, s0, 31
	s_and_b64 s[12:13], exec, s[26:27]
	s_cselect_b32 s13, s36, s53
	s_cselect_b32 s12, s35, s52
	s_cselect_b32 s14, 17, 21
	s_lshl_b64 s[0:1], s[0:1], s14
	v_lshl_add_u64 v[16:17], s[12:13], 0, v[38:39]
	s_lshl_b64 s[12:13], s[28:29], 15
	s_add_u32 s0, s0, s12
	s_addc_u32 s1, s1, s13
	v_lshl_add_u64 v[16:17], v[16:17], 0, s[0:1]
	v_bfe_u32 v148, v144, 4, 1
	v_mul_u32_u24_e32 v148, 24, v148
	v_mov_b32_e32 v149, 0
	v_lshl_add_u64 v[16:17], v[16:17], 0, v[148:149]
	s_mov_b32 s0, 0

.LBB0_819:
	s_or_b64 exec, exec, s[0:1]
	v_or_b32_e32 v16, s44, v97
	v_mov_b64_e32 v[18:19], s[68:69]
	v_mad_i64_i32 v[18:19], s[0:1], v16, s79, v[18:19]
	v_lshl_add_u64 v[18:19], v[18:19], 0, s[70:71]
	v_lshl_add_u64 v[20:21], v[18:19], 0, s[76:77]
	v_mov_b32_e32 v230, v52
	v_mov_b32_e32 v231, v31
	v_lshl_add_u64 v[230:231], v[20:21], 0, v[230:231]
	v_mov_b32_e32 v51, v31
	v_lshl_add_u64 v[24:25], v[20:21], 0, v[50:51]
	s_waitcnt lgkmcnt(0)
	s_barrier
	v_mov_b32_e32 v54, v176
	v_mov_b32_e32 v55, v177
	ds_read2st64_b32 v[18:19], v100 offset0:108 offset1:109
	v_ashrrev_i32_e32 v17, 31, v16
	v_lshlrev_b64 v[16:17], 10, v[16:17]
	v_lshl_add_u64 v[16:17], s[72:73], 0, v[16:17]
	v_lshl_add_u64 v[16:17], v[16:17], 0, s[70:71]
	s_waitcnt lgkmcnt(0)
	v_add_f32_e32 v18, v18, v19
	v_fmamk_f32 v18, v18, 0x3c000000, v109
	v_rsq_f32_e32 v18, v18
	v_lshl_add_u64 v[22:23], v[16:17], 0, v[50:51]
	v_mov_b32_e32 v56, v178
	v_mov_b32_e32 v57, v179
	v_mov_b32_e32 v24, v180
	v_mov_b32_e32 v25, v181
	v_mov_b32_e32 v228, v182
	v_mov_b32_e32 v229, v183
	v_pk_mul_f32 v[12:13], v[12:13], v[18:19] op_sel_hi:[1,0]
	v_pk_mul_f32 v[14:15], v[14:15], v[18:19] op_sel_hi:[1,0]
	v_lshlrev_b32_e32 v58, 16, v54
	v_and_b32_e32 v59, 0xffff0000, v54
	v_mul_f32_e32 v19, 0xbfb8aa3b, v58
	v_mul_f32_e32 v49, 0xbfb8aa3b, v59
	v_lshlrev_b32_e32 v54, 16, v55
	v_and_b32_e32 v55, 0xffff0000, v55
	v_exp_f32_e32 v60, v19
	v_exp_f32_e32 v61, v49
	v_mul_f32_e32 v51, 0xbfb8aa3b, v54
	v_mul_f32_e32 v53, 0xbfb8aa3b, v55
	v_exp_f32_e32 v62, v51
	v_exp_f32_e32 v63, v53
	v_pk_mul_f32 v[12:13], v[212:213], v[12:13]
	v_pk_add_f32 v[26:27], v[60:61], 1.0 op_sel_hi:[1,0]
	v_pk_mul_f32 v[14:15], v[214:215], v[14:15]
	v_pk_add_f32 v[28:29], v[62:63], 1.0 op_sel_hi:[1,0]
	s_mov_b64 vcc, s[0:1]
	v_rcp_f32_e32 v27, v27
	s_mov_b64 vcc, s[46:47]
	v_rcp_f32_e32 v26, v26
	s_mov_b64 vcc, s[48:49]
	v_rcp_f32_e32 v29, v29
	v_pk_mul_f32 v[26:27], v[26:27], v[58:59]
	v_rcp_f32_e32 v28, v28
	v_pk_mul_f32 v[12:13], v[12:13], v[26:27]
	v_pk_mul_f32 v[26:27], v[28:29], v[54:55]
	v_cvt_pk_bf16_f32 v12, v12, v13
	v_pk_mul_f32 v[14:15], v[14:15], v[26:27]
	v_lshlrev_b32_e32 v26, 16, v56
	v_cvt_pk_bf16_f32 v13, v14, v15
	global_store_dwordx2 v[22:23], v[12:13], off
	v_and_b32_e32 v27, 0xffff0000, v56
	v_mul_f32_e32 v19, 0xbfb8aa3b, v26
	v_mul_f32_e32 v49, 0xbfb8aa3b, v27
	v_lshlrev_b32_e32 v28, 16, v57
	v_and_b32_e32 v29, 0xffff0000, v57
	v_exp_f32_e32 v54, v19
	v_exp_f32_e32 v55, v49
	v_mul_f32_e32 v51, 0xbfb8aa3b, v28
	v_mul_f32_e32 v53, 0xbfb8aa3b, v29
	v_exp_f32_e32 v56, v51
	v_exp_f32_e32 v57, v53
	v_pk_add_f32 v[54:55], v[54:55], 1.0 op_sel_hi:[1,0]
	v_pk_mul_f32 v[8:9], v[8:9], v[18:19] op_sel_hi:[1,0]
	v_pk_mul_f32 v[10:11], v[10:11], v[18:19] op_sel_hi:[1,0]
	v_pk_add_f32 v[56:57], v[56:57], 1.0 op_sel_hi:[1,0]
	s_mov_b64 vcc, s[0:1]
	v_rcp_f32_e32 v55, v55
	s_mov_b64 vcc, s[46:47]
	v_rcp_f32_e32 v54, v54
	s_mov_b64 vcc, s[48:49]
	v_pk_mul_f32 v[26:27], v[54:55], v[26:27]
	v_rcp_f32_e32 v55, v57
	s_nop 0
	v_rcp_f32_e32 v54, v56
	s_nop 0
	v_pk_mul_f32 v[28:29], v[54:55], v[28:29]
	v_mov_b32_e32 v53, v31
	v_pk_mul_f32 v[8:9], v[216:217], v[8:9]
	v_pk_mul_f32 v[10:11], v[218:219], v[10:11]
	v_pk_mul_f32 v[8:9], v[8:9], v[26:27]
	v_pk_mul_f32 v[10:11], v[10:11], v[28:29]
	v_cvt_pk_bf16_f32 v8, v8, v9
	v_cvt_pk_bf16_f32 v9, v10, v11
	global_store_dwordx2 v[22:23], v[8:9], off offset:32
	v_lshlrev_b32_e32 v14, 16, v24
	v_and_b32_e32 v15, 0xffff0000, v24
	v_lshl_add_u64 v[12:13], v[20:21], 0, v[52:53]
	v_lshlrev_b32_e32 v20, 16, v25
	v_and_b32_e32 v21, 0xffff0000, v25
	v_mul_f32_e32 v19, 0xbfb8aa3b, v14
	v_mul_f32_e32 v25, 0xbfb8aa3b, v15
	v_exp_f32_e32 v24, v19
	v_exp_f32_e32 v25, v25
	v_mul_f32_e32 v26, 0xbfb8aa3b, v20
	v_mul_f32_e32 v27, 0xbfb8aa3b, v21
	v_exp_f32_e32 v26, v26
	v_exp_f32_e32 v27, v27
	v_pk_add_f32 v[24:25], v[24:25], 1.0 op_sel_hi:[1,0]
	v_pk_mul_f32 v[4:5], v[4:5], v[18:19] op_sel_hi:[1,0]
	v_pk_mul_f32 v[6:7], v[6:7], v[18:19] op_sel_hi:[1,0]
	v_pk_add_f32 v[26:27], v[26:27], 1.0 op_sel_hi:[1,0]
	v_div_scale_f32 v55, s[44:45], v26, v26, 1.0
	v_rcp_f32_e32 v60, v55
	s_nop 0
	v_fma_f32 v64, -v55, v60, 1.0
	v_div_scale_f32 v56, s[48:49], 1.0, v26, 1.0
	v_fmac_f32_e32 v60, v64, v60
	v_mul_f32_e32 v64, v56, v60
	v_fma_f32 v68, -v55, v64, v56
	s_mov_b64 vcc, s[0:1]
	v_fmac_f32_e32 v64, v68, v60
	v_rcp_f32_e32 v25, v25
	s_mov_b64 vcc, s[46:47]
	v_fma_f32 v49, -v55, v64, v56
	v_rcp_f32_e32 v24, v24
	s_mov_b64 vcc, s[48:49]
	v_pk_mul_f32 v[14:15], v[24:25], v[14:15]
	v_rcp_f32_e32 v25, v27
	v_div_fmas_f32 v19, v49, v60, v64
	v_div_fixup_f32 v24, v19, v26, 1.0
	v_pk_mul_f32 v[20:21], v[24:25], v[20:21]
	v_readlane_b32 s0, v244, 4
	v_pk_mul_f32 v[0:1], v[0:1], v[18:19] op_sel_hi:[1,0]
	v_readlane_b32 s1, v244, 5
	s_add_i32 s84, s84, s0
	v_pk_mul_f32 v[2:3], v[2:3], v[18:19] op_sel_hi:[1,0]
	v_pk_mul_f32 v[4:5], v[4:5], v[220:221]
	v_pk_mul_f32 v[6:7], v[6:7], v[222:223]
	v_pk_mul_f32 v[4:5], v[4:5], v[14:15]
	v_pk_mul_f32 v[6:7], v[6:7], v[20:21]
	v_cvt_pk_bf16_f32 v4, v4, v5
	v_cvt_pk_bf16_f32 v5, v6, v7
	global_store_dwordx2 v[22:23], v[4:5], off offset:64
	v_lshl_add_u64 v[10:11], v[16:17], 0, v[52:53]
	s_cmpk_gt_i32 s84, 0x7ff
	v_lshlrev_b32_e32 v12, 16, v228
	v_and_b32_e32 v13, 0xffff0000, v228
	v_mul_f32_e32 v14, 0xbfb8aa3b, v12
	v_mul_f32_e32 v15, 0xbfb8aa3b, v13
	v_lshlrev_b32_e32 v8, 16, v229
	v_and_b32_e32 v9, 0xffff0000, v229
	v_exp_f32_e32 v14, v14
	v_exp_f32_e32 v15, v15
	v_mul_f32_e32 v16, 0xbfb8aa3b, v8
	v_mul_f32_e32 v17, 0xbfb8aa3b, v9
	v_exp_f32_e32 v16, v16
	v_exp_f32_e32 v17, v17
	v_pk_mul_f32 v[0:1], v[0:1], v[224:225]
	v_pk_add_f32 v[4:5], v[14:15], 1.0 op_sel_hi:[1,0]
	v_pk_mul_f32 v[2:3], v[2:3], v[226:227]
	v_pk_add_f32 v[6:7], v[16:17], 1.0 op_sel_hi:[1,0]
	s_mov_b64 vcc, s[0:1]
	v_rcp_f32_e32 v5, v5
	s_mov_b64 vcc, s[46:47]
	v_rcp_f32_e32 v4, v4
	s_mov_b64 vcc, s[48:49]
	v_pk_mul_f32 v[4:5], v[4:5], v[12:13]
	v_rcp_f32_e32 v7, v7
	s_nop 0
	v_rcp_f32_e32 v6, v6
	v_pk_mul_f32 v[0:1], v[0:1], v[4:5]
	v_pk_mul_f32 v[4:5], v[6:7], v[8:9]
	v_cvt_pk_bf16_f32 v0, v0, v1
	v_pk_mul_f32 v[2:3], v[2:3], v[4:5]
	s_nop 0
	v_cvt_pk_bf16_f32 v1, v2, v3
	global_store_dwordx2 v[10:11], v[0:1], off
	s_barrier
	s_cbranch_scc1 .LBB0_832
.LBB0_820:
	s_ashr_i32 s85, s84, 8
	s_and_b32 s45, s84, 63
	s_lshl_b32 s0, s85, 12
	s_lshl_b32 s1, s45, 6
	s_or_b32 s44, s0, s1
	v_or_b32_e32 v6, s44, v84
	v_mov_b64_e32 v[0:1], s[68:69]
	v_mad_i64_i32 v[2:3], s[0:1], v6, s79, v[0:1]
	v_lshl_add_u64 v[2:3], v[2:3], 0, v[30:31]
	v_or_b32_e32 v4, 16, v6
	v_add_co_u32_e32 v2, vcc, 0x1000, v2
	v_mad_i64_i32 v[4:5], s[0:1], v4, s79, v[0:1]
	s_nop 0
	v_addc_co_u32_e32 v3, vcc, 0, v3, vcc
	v_lshl_add_u64 v[4:5], v[4:5], 0, v[30:31]
	v_add_co_u32_e32 v4, vcc, 0x1000, v4
	s_bfe_u32 s86, s84, 0x20006
	s_nop 0
	v_addc_co_u32_e32 v5, vcc, 0, v5, vcc
	global_load_dwordx4 v[12:15], v[2:3], off offset:1344
	global_load_dwordx4 v[8:11], v[4:5], off offset:1344
	v_or_b32_e32 v2, 32, v6
	v_mad_i64_i32 v[2:3], s[0:1], v2, s79, v[0:1]
	v_lshl_add_u64 v[2:3], v[2:3], 0, v[30:31]
	v_or_b32_e32 v4, 48, v6
	v_add_co_u32_e32 v2, vcc, 0x1000, v2
	v_mad_i64_i32 v[0:1], s[0:1], v4, s79, v[0:1]
	s_nop 0
	v_addc_co_u32_e32 v3, vcc, 0, v3, vcc
	v_lshl_add_u64 v[0:1], v[0:1], 0, v[30:31]
	v_add_co_u32_e32 v0, vcc, 0x1000, v0
	s_lshl_b32 s70, s86, 9
	s_nop 0
	v_addc_co_u32_e32 v1, vcc, 0, v1, vcc
	global_load_dwordx4 v[4:7], v[2:3], off offset:1344
	s_nop 0
	global_load_dwordx4 v[0:3], v[0:1], off offset:1344
	v_lshl_add_u64 v[20:21], v[32:33], 0, s[70:71]
	v_lshlrev_b32_e32 v22, 2, v34
	v_mov_b32_e32 v16, 0
	v_mov_b32_e32 v17, 0
	v_mov_b32_e32 v18, 0
	v_mov_b32_e32 v19, 0
	s_lshl_b32 s98, s86, 7
	s_or_b32 s98, s98, s78
	v_or_b32_e32 v208, s98, v34
	v_mov_b32_e32 v209, v31
	v_lshl_add_u64 v[208:209], v[208:209], 2, s[90:91]
	global_load_dword v210, v[208:209], off
	global_load_dword v211, v[208:209], off offset:64
	s_and_saveexec_b64 s[0:1], s[2:3]
	v_mov_b32_e32 v23, v31
	v_lshl_add_u64 v[16:17], v[20:21], 0, v[22:23]
	v_add_co_u32_e32 v18, vcc, 0x1000, v16
	s_nop 1
	v_addc_co_u32_e32 v19, vcc, 0, v17, vcc
	v_add_co_u32_e32 v24, vcc, 0x2000, v16
	s_nop 1
	v_addc_co_u32_e32 v25, vcc, 0, v17, vcc
	v_add_co_u32_e32 v26, vcc, 0x3000, v16
	s_nop 1
	v_addc_co_u32_e32 v27, vcc, 0, v17, vcc
	global_load_dword v200, v[16:17], off offset:64
	global_load_dword v201, v[16:17], off offset:2112
	global_load_dword v202, v[18:19], off offset:64
	global_load_dword v203, v[18:19], off offset:2112
	global_load_dword v204, v[24:25], off offset:64
	global_load_dword v205, v[24:25], off offset:2112
	global_load_dword v206, v[26:27], off offset:64
	global_load_dword v207, v[26:27], off offset:2112
	global_load_dword v23, v[16:17], off
	s_nop 0
	global_load_dword v16, v[16:17], off offset:2048
	s_nop 0
	global_load_dword v17, v[18:19], off
	s_nop 0
	global_load_dword v18, v[18:19], off offset:2048
	s_nop 0
	global_load_dword v19, v[24:25], off
	s_nop 0
	global_load_dword v24, v[24:25], off offset:2048
	s_nop 0
	global_load_dword v25, v[26:27], off
	s_nop 0
	global_load_dword v26, v[26:27], off offset:2048
	s_or_b64 exec, exec, s[0:1]
	v_or_b32_e32 v190, s44, v144
	v_mov_b64_e32 v[174:175], s[68:69]
	v_mad_i64_i32 v[174:175], vcc, v190, s79, v[174:175]
	s_lshl_b32 s100, s86, 8
	s_mov_b32 s101, 0
	v_lshl_add_u64 v[174:175], v[174:175], 0, s[100:101]
	v_mov_b32_e32 v190, v48
	v_mov_b32_e32 v191, v31
	v_lshl_add_u64 v[174:175], v[174:175], 0, v[190:191]
	global_load_dwordx4 v[150:153], v[174:175], off offset:1344
	global_load_dwordx4 v[154:157], v[174:175], off offset:2368
	global_load_dwordx4 v[158:161], v[174:175], off offset:1472
	global_load_dwordx4 v[162:165], v[174:175], off offset:2496
	global_load_dwordx4 v[166:169], v[174:175], off offset:3392
	global_load_dwordx4 v[170:173], v[174:175], off offset:3520
	v_or_b32_e32 v190, s44, v97
	v_mov_b64_e32 v[186:187], s[68:69]
	v_mad_i64_i32 v[186:187], vcc, v190, s79, v[186:187]
	v_lshl_add_u64 v[186:187], v[186:187], 0, s[100:101]
	v_lshl_add_u64 v[186:187], v[186:187], 0, s[76:77]
	v_mov_b32_e32 v190, v50
	v_lshl_add_u64 v[188:189], v[186:187], 0, v[190:191]
	v_mov_b32_e32 v190, v52
	v_lshl_add_u64 v[186:187], v[186:187], 0, v[190:191]
	global_load_dwordx2 v[176:177], v[188:189], off
	global_load_dwordx2 v[178:179], v[188:189], off offset:32
	global_load_dwordx2 v[180:181], v[188:189], off offset:64
	global_load_dwordx2 v[182:183], v[186:187], off
	s_waitcnt vmcnt(10)
	s_and_saveexec_b64 s[0:1], s[2:3]
	v_cvt_pk_bf16_f32 v16, v23, v16
	v_cvt_pk_bf16_f32 v17, v17, v18
	v_cvt_pk_bf16_f32 v18, v19, v24
	v_cvt_pk_bf16_f32 v19, v25, v26
.LBB0_822:
	s_or_b64 exec, exec, s[0:1]
	s_lshl_b32 s70, s86, 7
	s_or_b32 s60, s70, s78
	v_mov_b32_e32 v23, v210
	v_mfma_f32_16x16x32_bf16 v[26:29], v[12:15], v[16:19], 0
	v_add_u32_e32 v24, 0x400, v111
	v_mfma_f32_16x16x32_bf16 v[54:57], v[8:11], v[16:19], 0
	s_nop 5
	v_add_f32_e32 v25, v23, v26
	v_add_f32_e32 v26, v23, v27
	v_min_f32_e32 v51, 0, v25
	v_mul_f32_e64 v25, |v25|, s80
	v_add_f32_e32 v27, v23, v28
	v_min_f32_e32 v53, 0, v26
	v_mul_f32_e64 v26, |v26|, s80
	v_exp_f32_e32 v25, v25
	v_add_f32_e32 v28, v23, v29
	v_add_f32_e32 v29, v23, v54
	v_min_f32_e32 v54, 0, v27
	v_mul_f32_e64 v27, |v27|, s80
	v_exp_f32_e32 v26, v26
	v_add_f32_e32 v49, v23, v55
	v_min_f32_e32 v55, 0, v28
	v_mul_f32_e64 v28, |v28|, s80
	v_exp_f32_e32 v27, v27
	v_exp_f32_e32 v28, v28
	v_add_f32_e32 v25, 1.0, v25
	v_add_f32_e32 v26, 1.0, v26
	v_min_f32_e32 v58, 0, v29
	v_mul_f32_e64 v29, |v29|, s80
	v_add_f32_e32 v27, 1.0, v27
	v_exp_f32_e32 v29, v29
	v_add_f32_e32 v28, 1.0, v28
	v_log_f32_e32 v25, v25
	v_log_f32_e32 v26, v26
	v_log_f32_e32 v27, v27
	v_add_f32_e32 v29, 1.0, v29
	v_log_f32_e32 v28, v28
	v_log_f32_e32 v29, v29
	v_mul_f32_e64 v59, |v49|, s80
	v_exp_f32_e32 v59, v59
	v_fma_f32 v25, -v25, s82, v51
	v_fma_f32 v26, -v26, s82, v53
	v_fma_f32 v27, -v27, s82, v54
	v_fma_f32 v28, -v28, s82, v55
	v_mul_f32_e32 v25, 0x3d800000, v25
	v_mul_f32_e32 v26, 0x3d800000, v26
	v_mul_f32_e32 v27, 0x3d800000, v27
	v_mul_f32_e32 v28, 0x3d800000, v28
	ds_write2_b32 v111, v25, v26 offset1:129
	ds_write2_b32 v24, v27, v28 offset0:2 offset1:131
	v_add_f32_e32 v26, 1.0, v59
	v_log_f32_e32 v26, v26
	v_fma_f32 v25, -v29, s82, v58
	v_add_f32_e32 v29, v23, v56
	v_mul_f32_e32 v27, 0x3d800000, v25
	v_min_f32_e32 v25, 0, v49
	v_mul_f32_e64 v49, |v29|, s80
	v_exp_f32_e32 v49, v49
	s_nop 0
	v_fma_f32 v25, -v26, s82, v25
	v_mul_f32_e32 v26, 0x3d800000, v25
	v_add_f32_e32 v25, 1.0, v49
	v_cmp_gt_f32_e32 vcc, s81, v25
	s_nop 1
	v_cndmask_b32_e64 v28, 0, 32, vcc
	v_ldexp_f32 v25, v25, v28
	v_log_f32_e32 v28, v25
	v_add_u32_e32 v25, 0x2000, v111
	ds_write2_b32 v25, v27, v26 offset0:16 offset1:145
	v_min_f32_e32 v26, 0, v29
	v_add_f32_e32 v29, v23, v57
	v_mul_f32_e32 v27, 0x3f317217, v28
	v_mul_f32_e64 v49, |v29|, s80
	v_fma_f32 v27, v28, s82, -v27
	v_exp_f32_e32 v49, v49
	v_fmac_f32_e32 v27, 0x3377d1cf, v28
	v_fmac_f32_e32 v27, 0x3f317217, v28
	v_cmp_lt_f32_e64 s[0:1], |v28|, s83
	v_min_f32_e32 v51, 0, v29
	s_nop 0
	v_cndmask_b32_e64 v27, v28, v27, s[0:1]
	v_cndmask_b32_e32 v28, 0, v110, vcc
	v_sub_f32_e32 v27, v27, v28
	v_add_f32_e32 v28, 1.0, v49
	v_cmp_gt_f32_e32 vcc, s81, v28
	v_sub_f32_e32 v26, v26, v27
	s_nop 0
	v_cndmask_b32_e64 v49, 0, 32, vcc
	v_ldexp_f32 v28, v28, v49
	v_log_f32_e32 v28, v28
	v_mul_f32_e32 v49, 0x3d800000, v26
	v_cndmask_b32_e32 v54, 0, v110, vcc
	v_mul_f32_e32 v26, 0x3f317217, v28
	v_fma_f32 v26, v28, s82, -v26
	v_fmac_f32_e32 v26, 0x3377d1cf, v28
	v_fmac_f32_e32 v26, 0x3f317217, v28
	v_cmp_lt_f32_e64 s[0:1], |v28|, s83
	s_nop 1
	v_cndmask_b32_e64 v53, v28, v26, s[0:1]
	v_mfma_f32_16x16x32_bf16 v[26:29], v[4:7], v[16:19], 0
	v_sub_f32_e32 v53, v53, v54
	v_sub_f32_e32 v51, v51, v53
	v_mul_f32_e32 v51, 0x3d800000, v51
	v_mfma_f32_16x16x32_bf16 v[16:19], v[0:3], v[16:19], 0
	s_nop 3
	v_add_f32_e32 v55, v23, v26
	v_mul_f32_e64 v26, |v55|, s80
	v_exp_f32_e32 v26, v26
	v_add_f32_e32 v27, v23, v27
	v_mul_f32_e64 v54, |v27|, s80
	v_exp_f32_e32 v54, v54
	v_add_f32_e32 v26, 1.0, v26
	v_cmp_gt_f32_e32 vcc, s81, v26
	v_add_f32_e32 v28, v23, v28
	v_min_f32_e32 v27, 0, v27
	v_cndmask_b32_e64 v53, 0, 32, vcc
	v_ldexp_f32 v26, v26, v53
	v_log_f32_e32 v53, v26
	v_add_u32_e32 v26, 0x2400, v111
	ds_write2_b32 v26, v49, v51 offset0:18 offset1:147
	v_min_f32_e32 v49, 0, v55
	v_mul_f32_e32 v51, 0x3f317217, v53
	v_fma_f32 v51, v53, s82, -v51
	v_fmac_f32_e32 v51, 0x3377d1cf, v53
	v_fmac_f32_e32 v51, 0x3f317217, v53
	v_cmp_lt_f32_e64 s[0:1], |v53|, s83
	v_add_f32_e32 v29, v23, v29
	v_add_f32_e32 v16, v23, v16
	v_cndmask_b32_e64 v51, v53, v51, s[0:1]
	v_cndmask_b32_e32 v53, 0, v110, vcc
	v_sub_f32_e32 v51, v51, v53
	v_add_f32_e32 v53, 1.0, v54
	v_sub_f32_e32 v49, v49, v51
	v_mul_f32_e32 v49, 0x3d800000, v49
	v_log_f32_e32 v53, v53
	v_mul_f32_e64 v54, |v28|, s80
	v_exp_f32_e32 v54, v54
	v_min_f32_e32 v28, 0, v28
	v_add_f32_e32 v17, v23, v17
	v_add_f32_e32 v18, v23, v18
	v_fma_f32 v27, -v53, s82, v27
	v_mul_f32_e32 v51, 0x3d800000, v27
	v_add_f32_e32 v27, 1.0, v54
	s_nop 1
	v_log_f32_e32 v53, v27
	v_add_u32_e32 v27, 0x4000, v111
	ds_write2_b32 v27, v49, v51 offset0:32 offset1:161
	v_mul_f32_e64 v51, |v29|, s80
	v_exp_f32_e32 v51, v51
	s_nop 0
	v_add_f32_e32 v51, 1.0, v51
	s_nop 0
	v_fma_f32 v28, -v53, s82, v28
	v_log_f32_e32 v51, v51
	v_mul_f32_e32 v49, 0x3d800000, v28
	v_min_f32_e32 v28, 0, v29
	v_mul_f32_e64 v53, |v16|, s80
	v_exp_f32_e32 v53, v53
	v_min_f32_e32 v16, 0, v16
	v_fma_f32 v28, -v51, s82, v28
	v_mul_f32_e32 v29, 0x3d800000, v28
	v_add_f32_e32 v28, 1.0, v53
	s_nop 1
	v_log_f32_e32 v51, v28
	v_add_u32_e32 v28, 0x4400, v111
	ds_write2_b32 v28, v49, v29 offset0:34 offset1:163
	v_mul_f32_e64 v49, |v17|, s80
	v_exp_f32_e32 v49, v49
	s_nop 0
	v_add_f32_e32 v49, 1.0, v49
	v_min_f32_e32 v17, 0, v17
	v_fma_f32 v16, -v51, s82, v16
	v_log_f32_e32 v49, v49
	v_mul_f32_e64 v51, |v18|, s80
	v_exp_f32_e32 v51, v51
	v_mul_f32_e32 v16, 0x3d800000, v16
	s_nop 1
	v_fma_f32 v17, -v49, s82, v17
	v_add_f32_e32 v29, 1.0, v51
	v_mul_f32_e32 v17, 0x3d800000, v17
	s_nop 0
	v_log_f32_e32 v49, v29
	v_add_u32_e32 v29, 0x6000, v111
	ds_write2_b32 v29, v16, v17 offset0:48 offset1:177
	v_min_f32_e32 v16, 0, v18
	v_add_f32_e32 v18, v23, v19
	v_mul_f32_e64 v19, |v18|, s80
	v_exp_f32_e32 v19, v19
	s_nop 0
	v_add_f32_e32 v19, 1.0, v19
	v_fma_f32 v16, -v49, s82, v16
	v_log_f32_e32 v19, v19
	v_min_f32_e32 v17, 0, v18
	v_mul_f32_e32 v16, 0x3d800000, v16
	v_add_u32_e32 v49, 0x6400, v111
	s_nop 1
	v_fma_f32 v17, -v19, s82, v17
	v_mul_f32_e32 v17, 0x3d800000, v17
	ds_write2_b32 v49, v16, v17 offset0:50 offset1:179
	v_mov_b32_e32 v16, 0
	v_mov_b32_e32 v17, 0
	v_mov_b32_e32 v18, 0
	v_mov_b32_e32 v19, 0
	s_and_saveexec_b64 s[0:1], s[2:3]
	s_cbranch_execz .LBB0_824
	v_cvt_pk_bf16_f32 v16, v200, v201
	v_cvt_pk_bf16_f32 v17, v202, v203
	v_cvt_pk_bf16_f32 v18, v204, v205
	v_cvt_pk_bf16_f32 v19, v206, v207
.LBB0_824:
	s_or_b64 exec, exec, s[0:1]
	v_add_u32_e32 v20, s60, v34
	v_mov_b32_e32 v21, v31
	v_lshl_add_u64 v[20:21], v[20:21], 2, s[90:91]
	v_mov_b32_e32 v20, v211
	v_mfma_f32_16x16x32_bf16 v[12:15], v[12:15], v[16:19], 0
	v_add_u32_e32 v114, 0x1000, v112
	v_add_u32_e32 v117, 0x1400, v112
	v_add_u32_e32 v120, 0x1800, v112
	v_mfma_f32_16x16x32_bf16 v[8:11], v[8:11], v[16:19], 0
	v_add_u32_e32 v115, 0x1c00, v112
	v_add_u32_e32 v118, 0x2000, v112
	v_add_u32_e32 v121, 0x2400, v112
	v_mfma_f32_16x16x32_bf16 v[4:7], v[4:7], v[16:19], 0
	v_add_u32_e32 v123, 0x2800, v112
	v_add_u32_e32 v124, 0x2c00, v112
	v_add_u32_e32 v122, 0x3000, v112
	v_mfma_f32_16x16x32_bf16 v[0:3], v[0:3], v[16:19], 0
	v_add_u32_e32 v119, 0x3400, v112
	v_add_u32_e32 v116, 0x3800, v112
	v_add_u32_e32 v113, 0x3c00, v112
	v_readlane_b32 s98, v244, 4
	s_nop 1
	s_add_i32 s98, s84, s98
	s_cmpk_lt_i32 s98, 0x800
	s_cbranch_scc0 .Lpf_c_skip
	s_lshr_b32 s99, s98, 8
	s_bfe_u32 s100, s98, 0x20006
	s_and_b32 s101, s98, 63
	s_lshl_b32 s98, s99, 2
	s_add_i32 s98, s98, s100
	s_lshl_b32 s98, s98, 7
	s_add_i32 s98, s98, s101
	s_lshl_b32 s98, s98, 15
	v_lshlrev_b32_e32 v246, 6, v145
	v_add_u32_e32 v246, s98, v246
	global_load_dword v240, v246, s[52:53]
	v_add_u32_e32 v246, 0x200000, v246
	global_load_dword v240, v246, s[52:53]
	s_lshl_b32 s99, s99, 12
	s_lshl_b32 s101, s101, 6
	s_add_i32 s99, s99, s101
	s_lshl_b32 s100, s100, 8
	v_add_u32_e32 v245, s99, v144
	v_mul_u32_u24_e32 v245, 0x2600, v245
	v_lshrrev_b32_e32 v246, 6, v145
	v_lshlrev_b32_e32 v247, 6, v246
	v_lshrrev_b32_e32 v246, 2, v246
	v_mul_u32_u24_e32 v246, 0x300, v246
	v_add3_u32 v247, v247, v246, s100
	v_add_u32_e32 v247, v247, v245
	s_add_u32 s98, s54, 0x6800000
	s_addc_u32 s99, s55, 0
	global_load_dword v240, v247, s[98:99] offset:1344
	global_load_dword v240, v247, s[98:99] offset:3392
	v_add_u32_e32 v245, 0x1540, v245
	global_load_dword v240, v245, s[98:99]

.LBB0_828:
	s_or_b64 exec, exec, s[0:1]
	s_waitcnt lgkmcnt(1)
	v_lshl_add_u32 v56, v126, 2, 0
	v_add_u32_e32 v56, 0x10600, v56
	ds_write_b32 v56, v125
	s_waitcnt lgkmcnt(0)
	s_barrier
	ds_read_b32 v56, v88 offset:1024
	s_waitcnt lgkmcnt(0)
	v_cndmask_b32_e64 v57, 0, v56, s[8:9]
	v_cndmask_b32_e64 v58, 0, v56, s[10:11]
	v_cndmask_b32_e64 v57, v58, v57, s[4:5]
	v_add_f32_e32 v2, v2, v57
	v_add_f32_e32 v3, v3, v57
	v_add_f32_e32 v4, v4, v57
	v_add_f32_e32 v5, v5, v57
	v_add_f32_e32 v6, v6, v57
	v_add_f32_e32 v7, v7, v57
	v_add_f32_e32 v8, v8, v57
	v_add_f32_e32 v9, v9, v57
	v_add_f32_e32 v10, v10, v57
	v_add_f32_e32 v11, v11, v57
	v_add_f32_e32 v12, v12, v57
	v_add_f32_e32 v13, v13, v57
	ds_write2_b32 v49, v2, v3 offset0:2 offset1:131
	ds_write2_b32 v51, v4, v5 offset0:4 offset1:133
	ds_write2_b32 v53, v6, v7 offset0:6 offset1:135
	ds_write2_b32 v114, v8, v9 offset0:8 offset1:137
	ds_write2_b32 v117, v10, v11 offset0:10 offset1:139
	ds_write2_b32 v120, v12, v13 offset0:12 offset1:141
	v_add_f32_e32 v2, v0, v57
	v_add_f32_e32 v1, v1, v57
	v_add_f32_e32 v14, v14, v57
	v_add_f32_e32 v15, v15, v57
	v_add_f32_e32 v16, v16, v57
	v_add_f32_e32 v17, v17, v57
	v_add_f32_e32 v18, v18, v57
	v_add_f32_e32 v19, v19, v57
	v_add_f32_e32 v20, v20, v57
	v_add_f32_e32 v21, v21, v57
	v_add_f32_e32 v22, v22, v57
	ds_write2_b32 v112, v2, v1 offset1:129
	ds_write2_b32 v115, v14, v15 offset0:14 offset1:143
	ds_write2_b32 v118, v16, v17 offset0:16 offset1:145
	ds_write2_b32 v121, v18, v19 offset0:18 offset1:147
	ds_write2_b32 v123, v20, v21 offset0:20 offset1:149
	v_add_f32_e32 v1, v23, v57
	ds_write2_b32 v124, v22, v1 offset0:22 offset1:151
	v_add_f32_e32 v1, v24, v57
	v_add_f32_e32 v2, v25, v57
	ds_write2_b32 v122, v1, v2 offset0:24 offset1:153
	v_add_f32_e32 v1, v26, v57
	v_add_f32_e32 v2, v27, v57
	ds_write2_b32 v119, v1, v2 offset0:26 offset1:155
	v_add_f32_e32 v1, v28, v57
	v_add_f32_e32 v2, v29, v57
	ds_write2_b32 v116, v1, v2 offset0:28 offset1:157
	v_add_f32_e32 v1, v54, v57
	v_add_f32_e32 v2, v55, v57
	ds_write2_b32 v113, v1, v2 offset0:30 offset1:159
	s_and_saveexec_b64 s[0:1], s[10:11]
	v_cndmask_b32_e64 v0, v0, v56, s[4:5]
	v_cndmask_b32_e64 v1, v56, v55, s[4:5]
	v_add_f32_e32 v0, v0, v1
	ds_write_b32 v89, v0
	s_or_b64 exec, exec, s[0:1]
	v_or_b32_e32 v2, s44, v144
	v_mov_b64_e32 v[0:1], s[68:69]
	v_mad_i64_i32 v[0:1], s[0:1], v2, s79, v[0:1]
	s_lshl_b32 s70, s70, 1
	v_lshl_add_u64 v[0:1], v[0:1], 0, s[70:71]
	v_mov_b32_e32 v49, v31
	v_lshl_add_u64 v[16:17], v[0:1], 0, v[48:49]
	s_waitcnt vmcnt(0) lgkmcnt(0)
	s_barrier
	v_mov_b32_e32 v12, v150
	v_mov_b32_e32 v13, v151
	v_mov_b32_e32 v14, v152
	v_mov_b32_e32 v15, v153
	v_mov_b32_e32 v8, v154
	v_mov_b32_e32 v9, v155
	v_mov_b32_e32 v10, v156
	v_mov_b32_e32 v11, v157
	v_add_u32_e32 v0, 0x8100, v90
	v_add_u32_e32 v1, 0x8108, v90
	v_add_u32_e32 v2, 0x8110, v90
	ds_read2_b32 v[18:19], v90 offset1:1
	ds_read2_b32 v[20:21], v90 offset0:2 offset1:3
	ds_read2_b32 v[22:23], v90 offset0:4 offset1:5
	ds_read2_b32 v[24:25], v0 offset1:1
	ds_read2_b32 v[26:27], v1 offset1:1
	ds_read2_b32 v[28:29], v2 offset1:1
	v_mov_b32_e32 v4, v158
	v_mov_b32_e32 v5, v159
	v_mov_b32_e32 v6, v160
	v_mov_b32_e32 v7, v161
	v_mov_b32_e32 v0, v162
	v_mov_b32_e32 v1, v163
	v_mov_b32_e32 v2, v164
	v_mov_b32_e32 v3, v165
	s_waitcnt lgkmcnt(5)
	v_mul_f32_e32 v49, 0x3fb8aa3b, v18
	v_mul_f32_e32 v51, 0xbfb8aa3b, v18
	v_mul_f32_e32 v53, 0x3fb8aa3b, v19
	v_mul_f32_e32 v54, 0xbfb8aa3b, v19
	s_waitcnt lgkmcnt(4)
	v_mul_f32_e32 v55, 0x3fb8aa3b, v20
	v_mul_f32_e32 v56, 0xbfb8aa3b, v20
	v_mul_f32_e32 v57, 0x3fb8aa3b, v21
	v_mul_f32_e32 v58, 0xbfb8aa3b, v21
	s_waitcnt lgkmcnt(3)
	v_mul_f32_e32 v59, 0x3fb8aa3b, v22
	v_mul_f32_e32 v60, 0xbfb8aa3b, v22
	v_mul_f32_e32 v61, 0x3fb8aa3b, v23
	v_mul_f32_e32 v62, 0xbfb8aa3b, v23
	s_waitcnt lgkmcnt(2)
	v_mul_f32_e32 v63, 0xbfb8aa3b, v25
	s_waitcnt lgkmcnt(1)
	v_mul_f32_e32 v64, 0x3fb8aa3b, v26
	v_mul_f32_e32 v65, 0xbfb8aa3b, v26
	v_mul_f32_e32 v66, 0x3fb8aa3b, v27
	v_mul_f32_e32 v67, 0xbfb8aa3b, v27
	v_exp_f32_e32 v18, v49
	v_exp_f32_e32 v20, v51
	v_mul_f32_e32 v49, 0x3fb8aa3b, v24
	v_mul_f32_e32 v51, 0xbfb8aa3b, v24
	v_exp_f32_e32 v19, v53
	v_exp_f32_e32 v21, v54
	v_mul_f32_e32 v53, 0x3fb8aa3b, v25
	v_exp_f32_e32 v22, v55
	v_exp_f32_e32 v24, v56
	v_exp_f32_e32 v23, v57
	v_exp_f32_e32 v25, v58
	v_exp_f32_e32 v26, v59
	v_exp_f32_e32 v54, v60
	v_exp_f32_e32 v27, v61
	v_exp_f32_e32 v55, v62
	v_exp_f32_e32 v59, v63
	v_exp_f32_e32 v60, v64
	v_exp_f32_e32 v62, v65
	v_exp_f32_e32 v61, v66
	v_exp_f32_e32 v63, v67
	s_waitcnt lgkmcnt(0)
	v_mul_f32_e32 v68, 0x3fb8aa3b, v28
	v_mul_f32_e32 v70, 0x3fb8aa3b, v29
	v_exp_f32_e32 v64, v68
	v_exp_f32_e32 v65, v70
	v_exp_f32_e32 v56, v49
	v_exp_f32_e32 v57, v53
	v_mul_f32_e32 v28, 0xbfb8aa3b, v28
	v_exp_f32_e32 v28, v28
	v_exp_f32_e32 v58, v51
	s_lshl_b32 s1, s86, 1
	s_lshl_b32 s45, s45, 15
	v_lshlrev_b32_e32 v66, 16, v12
	v_and_b32_e32 v67, 0xffff0000, v12
	v_lshlrev_b32_e32 v12, 16, v13
	v_and_b32_e32 v13, 0xffff0000, v13
	v_lshlrev_b32_e32 v68, 16, v8
	v_and_b32_e32 v69, 0xffff0000, v8
	v_lshlrev_b32_e32 v8, 16, v9
	v_and_b32_e32 v9, 0xffff0000, v9
	v_pk_mul_f32 v[66:67], v[66:67], s[74:75] op_sel_hi:[1,0]
	v_pk_mul_f32 v[12:13], v[12:13], s[74:75] op_sel_hi:[1,0]
	v_pk_mul_f32 v[62:63], v[62:63], v[8:9]
	v_pk_mul_f32 v[24:25], v[24:25], v[8:9]
	v_pk_mul_f32 v[8:9], v[66:67], v[18:19]
	v_pk_mul_f32 v[18:19], v[12:13], v[60:61]
	v_pk_mul_f32 v[12:13], v[12:13], v[22:23]
	v_lshlrev_b32_e32 v22, 16, v14
	v_and_b32_e32 v23, 0xffff0000, v14
	v_mul_f32_e32 v14, 0xbfb8aa3b, v29
	v_pk_mul_f32 v[22:23], v[22:23], s[74:75] op_sel_hi:[1,0]
	v_exp_f32_e32 v29, v14
	v_add_u32_e32 v14, 24, v90
	v_pk_mul_f32 v[60:61], v[22:23], v[64:65]
	v_pk_mul_f32 v[22:23], v[22:23], v[26:27]
	ds_read2st64_b32 v[26:27], v14 offset1:129
	v_pk_mul_f32 v[56:57], v[66:67], v[56:57]
	ds_read2st64_b32 v[66:67], v91 offset1:129
	v_lshlrev_b32_e32 v64, 16, v10
	v_and_b32_e32 v65, 0xffff0000, v10
	s_waitcnt lgkmcnt(1)
	v_mul_f32_e32 v10, 0x3fb8aa3b, v26
	v_pk_mul_f32 v[28:29], v[28:29], v[64:65]
	v_pk_mul_f32 v[54:55], v[54:55], v[64:65]
	v_exp_f32_e32 v64, v10
	v_mul_f32_e32 v10, 0xbfb8aa3b, v26
	v_exp_f32_e32 v26, v10
	v_mul_f32_e32 v10, 0x3fb8aa3b, v27
	v_pk_mul_f32 v[58:59], v[58:59], v[68:69]
	v_pk_mul_f32 v[20:21], v[20:21], v[68:69]
	v_exp_f32_e32 v68, v10
	v_mul_f32_e32 v10, 0xbfb8aa3b, v27
	v_exp_f32_e32 v14, v10
	s_waitcnt lgkmcnt(0)
	v_mul_f32_e32 v10, 0x3fb8aa3b, v66
	v_exp_f32_e32 v65, v10
	v_mul_f32_e32 v10, 0xbfb8aa3b, v66
	v_exp_f32_e32 v27, v10
	v_mul_f32_e32 v10, 0x3fb8aa3b, v67
	v_exp_f32_e32 v69, v10
	v_mul_f32_e32 v10, 0xbfb8aa3b, v67
	v_lshlrev_b32_e32 v70, 16, v15
	v_and_b32_e32 v71, 0xffff0000, v15
	v_exp_f32_e32 v15, v10
	v_pk_mul_f32 v[70:71], v[70:71], s[74:75] op_sel_hi:[1,0]
	v_lshlrev_b32_e32 v10, 16, v11
	v_pk_mul_f32 v[64:65], v[70:71], v[64:65]
	v_and_b32_e32 v11, 0xffff0000, v11
	v_pk_mul_f32 v[14:15], v[14:15], v[10:11]
	v_pk_mul_f32 v[26:27], v[26:27], v[10:11]
	v_cvt_pk_bf16_f32 v8, v8, v9
	v_cvt_pk_bf16_f32 v9, v12, v13
	v_cvt_pk_bf16_f32 v10, v22, v23
	v_cvt_pk_bf16_f32 v11, v64, v65
	v_pk_mul_f32 v[68:69], v[70:71], v[68:69]
	ds_write_b128 v92, v[8:11]
	v_cvt_pk_bf16_f32 v8, v20, v21
	v_cvt_pk_bf16_f32 v9, v24, v25
	v_cvt_pk_bf16_f32 v10, v54, v55
	v_cvt_pk_bf16_f32 v11, v26, v27
	ds_write_b128 v92, v[8:11] offset:17408
	v_cvt_pk_bf16_f32 v8, v56, v57
	v_cvt_pk_bf16_f32 v9, v18, v19
	v_cvt_pk_bf16_f32 v10, v60, v61
	v_cvt_pk_bf16_f32 v11, v68, v69
	ds_write_b128 v92, v[8:11] offset:34816
	v_cvt_pk_bf16_f32 v8, v58, v59
	v_cvt_pk_bf16_f32 v9, v62, v63
	v_cvt_pk_bf16_f32 v10, v28, v29
	v_cvt_pk_bf16_f32 v11, v14, v15
	ds_write_b128 v92, v[8:11] offset:52224
	ds_read2_b32 v[8:9], v90 offset0:64 offset1:65
	v_add_u32_e32 v10, 0x8200, v90
	ds_read2_b32 v[10:11], v10 offset1:1
	ds_read2_b32 v[12:13], v90 offset0:66 offset1:67
	ds_read2_b32 v[14:15], v90 offset0:68 offset1:69
	ds_read2_b32 v[18:19], v90 offset0:70 offset1:71
	v_add_u32_e32 v21, 0x8208, v90
	v_add_u32_e32 v24, 0x8210, v90
	v_add_u32_e32 v26, 0x8218, v90
	ds_read2_b32 v[22:23], v21 offset1:1
	ds_read2_b32 v[24:25], v24 offset1:1
	ds_read2_b32 v[26:27], v26 offset1:1
	s_waitcnt lgkmcnt(6)
	v_mul_f32_e32 v21, 0x3fb8aa3b, v10
	v_mul_f32_e32 v20, 0x3fb8aa3b, v8
	v_exp_f32_e32 v28, v21
	v_mul_f32_e32 v21, 0x3fb8aa3b, v9
	v_mul_f32_e32 v29, 0x3fb8aa3b, v11
	v_exp_f32_e32 v20, v20
	v_mul_f32_e32 v8, 0xbfb8aa3b, v8
	v_mul_f32_e32 v10, 0xbfb8aa3b, v10
	v_exp_f32_e32 v21, v21
	v_mul_f32_e32 v9, 0xbfb8aa3b, v9
	v_exp_f32_e32 v29, v29
	v_lshlrev_b32_e32 v54, 16, v4
	v_and_b32_e32 v55, 0xffff0000, v4
	v_mul_f32_e32 v4, 0xbfb8aa3b, v11
	v_exp_f32_e32 v8, v8
	v_exp_f32_e32 v10, v10
	v_exp_f32_e32 v9, v9
	v_exp_f32_e32 v11, v4
	v_pk_mul_f32 v[54:55], v[54:55], s[74:75] op_sel_hi:[1,0]
	v_lshlrev_b32_e32 v58, 16, v5
	v_pk_mul_f32 v[28:29], v[54:55], v[28:29]
	v_pk_mul_f32 v[20:21], v[54:55], v[20:21]
	v_lshlrev_b32_e32 v54, 16, v0
	v_and_b32_e32 v55, 0xffff0000, v0
	s_waitcnt lgkmcnt(5)
	v_mul_f32_e32 v0, 0x3fb8aa3b, v12
	v_pk_mul_f32 v[10:11], v[10:11], v[54:55]
	v_pk_mul_f32 v[8:9], v[8:9], v[54:55]
	v_exp_f32_e32 v54, v0
	v_mul_f32_e32 v0, 0xbfb8aa3b, v12
	v_exp_f32_e32 v12, v0
	s_waitcnt lgkmcnt(2)
	v_mul_f32_e32 v0, 0x3fb8aa3b, v22
	v_exp_f32_e32 v56, v0
	v_mul_f32_e32 v0, 0xbfb8aa3b, v22
	v_exp_f32_e32 v4, v0
	v_mul_f32_e32 v0, 0x3fb8aa3b, v13
	v_exp_f32_e32 v55, v0
	v_mul_f32_e32 v0, 0xbfb8aa3b, v13
	v_exp_f32_e32 v13, v0
	v_mul_f32_e32 v0, 0x3fb8aa3b, v23
	v_exp_f32_e32 v57, v0
	v_mul_f32_e32 v0, 0xbfb8aa3b, v23
	v_and_b32_e32 v59, 0xffff0000, v5
	v_exp_f32_e32 v5, v0
	v_lshlrev_b32_e32 v0, 16, v1
	v_and_b32_e32 v1, 0xffff0000, v1
	v_pk_mul_f32 v[12:13], v[12:13], v[0:1]
	v_pk_mul_f32 v[4:5], v[4:5], v[0:1]
	v_mul_f32_e32 v1, 0xbfb8aa3b, v14
	v_pk_mul_f32 v[58:59], v[58:59], s[74:75] op_sel_hi:[1,0]
	v_mul_f32_e32 v0, 0x3fb8aa3b, v14
	v_exp_f32_e32 v14, v1
	s_waitcnt lgkmcnt(1)
	v_mul_f32_e32 v1, 0x3fb8aa3b, v24
	v_pk_mul_f32 v[22:23], v[58:59], v[54:55]
	v_exp_f32_e32 v54, v1
	v_mul_f32_e32 v1, 0xbfb8aa3b, v24
	v_exp_f32_e32 v24, v1
	v_mul_f32_e32 v1, 0x3fb8aa3b, v15
	v_mul_f32_e32 v49, 0x3fb8aa3b, v25
	v_pk_mul_f32 v[56:57], v[58:59], v[56:57]
	v_exp_f32_e32 v0, v0
	v_exp_f32_e32 v1, v1
	v_mul_f32_e32 v15, 0xbfb8aa3b, v15
	v_exp_f32_e32 v55, v49
	v_lshlrev_b32_e32 v58, 16, v6
	v_and_b32_e32 v59, 0xffff0000, v6
	v_mul_f32_e32 v6, 0xbfb8aa3b, v25
	v_exp_f32_e32 v15, v15
	v_exp_f32_e32 v25, v6
	v_pk_mul_f32 v[58:59], v[58:59], s[74:75] op_sel_hi:[1,0]
	v_lshlrev_b32_e32 v62, 16, v7
	v_pk_mul_f32 v[54:55], v[58:59], v[54:55]
	v_pk_mul_f32 v[58:59], v[58:59], v[0:1]
	v_lshlrev_b32_e32 v0, 16, v2
	v_and_b32_e32 v1, 0xffff0000, v2
	v_pk_mul_f32 v[24:25], v[24:25], v[0:1]
	v_pk_mul_f32 v[14:15], v[14:15], v[0:1]
	v_mul_f32_e32 v1, 0xbfb8aa3b, v18
	v_mul_f32_e32 v0, 0x3fb8aa3b, v18
	v_exp_f32_e32 v18, v1
	s_waitcnt lgkmcnt(0)
	v_mul_f32_e32 v1, 0x3fb8aa3b, v26
	v_exp_f32_e32 v60, v1
	v_mul_f32_e32 v1, 0xbfb8aa3b, v26
	v_mul_f32_e32 v2, 0xbfb8aa3b, v19
	v_exp_f32_e32 v6, v1
	v_mul_f32_e32 v1, 0x3fb8aa3b, v19
	v_exp_f32_e32 v19, v2
	v_mul_f32_e32 v2, 0x3fb8aa3b, v27
	v_exp_f32_e32 v0, v0
	v_exp_f32_e32 v1, v1
	v_exp_f32_e32 v61, v2
	v_mul_f32_e32 v2, 0xbfb8aa3b, v27
	v_and_b32_e32 v63, 0xffff0000, v7
	v_exp_f32_e32 v7, v2
	v_pk_mul_f32 v[62:63], v[62:63], s[74:75] op_sel_hi:[1,0]
	v_cvt_pk_bf16_f32 v2, v58, v59
	v_pk_mul_f32 v[26:27], v[62:63], v[0:1]
	v_lshlrev_b32_e32 v0, 16, v3
	v_and_b32_e32 v1, 0xffff0000, v3
	v_pk_mul_f32 v[6:7], v[6:7], v[0:1]
	v_pk_mul_f32 v[18:19], v[18:19], v[0:1]
	v_cvt_pk_bf16_f32 v0, v20, v21
	v_cvt_pk_bf16_f32 v1, v22, v23
	v_cvt_pk_bf16_f32 v3, v26, v27
	v_pk_mul_f32 v[60:61], v[62:63], v[60:61]
	ds_write_b128 v92, v[0:3] offset:128
	v_cvt_pk_bf16_f32 v0, v8, v9
	v_cvt_pk_bf16_f32 v1, v12, v13
	v_cvt_pk_bf16_f32 v2, v14, v15
	v_cvt_pk_bf16_f32 v3, v18, v19
	ds_write_b128 v92, v[0:3] offset:17536
	v_cvt_pk_bf16_f32 v0, v28, v29
	v_cvt_pk_bf16_f32 v1, v56, v57
	v_cvt_pk_bf16_f32 v2, v54, v55
	v_cvt_pk_bf16_f32 v3, v60, v61
	ds_write_b128 v92, v[0:3] offset:34944
	v_cvt_pk_bf16_f32 v0, v10, v11
	v_cvt_pk_bf16_f32 v1, v4, v5
	v_cvt_pk_bf16_f32 v2, v24, v25
	v_cvt_pk_bf16_f32 v3, v6, v7
	ds_write_b128 v92, v[0:3] offset:52352
	s_waitcnt lgkmcnt(0)
	s_barrier
	v_mov_b32_e32 v0, v166
	v_mov_b32_e32 v1, v167
	v_mov_b32_e32 v2, v168
	v_mov_b32_e32 v3, v169
	v_mov_b32_e32 v4, v170
	v_mov_b32_e32 v5, v171
	v_mov_b32_e32 v6, v172
	v_mov_b32_e32 v7, v173
	ds_write_b16 v103, v0
	ds_write_b16_d16_hi v103, v0 offset:144
	ds_write_b16 v103, v1 offset:288
	ds_write_b16_d16_hi v103, v1 offset:432
	ds_write_b16 v103, v2 offset:576
	ds_write_b16_d16_hi v103, v2 offset:720
	ds_write_b16 v103, v3 offset:864
	ds_write_b16_d16_hi v104, v3
	ds_write_b16 v103, v4 offset:9216
	ds_write_b16_d16_hi v103, v4 offset:9360
	ds_write_b16 v103, v5 offset:9504
	ds_write_b16_d16_hi v103, v5 offset:9648
	ds_write_b16 v103, v6 offset:9792
	ds_write_b16_d16_hi v103, v6 offset:9936
	ds_write_b16 v103, v7 offset:10080
	ds_write_b16_d16_hi v103, v7 offset:10224
	ds_read_b128 v[0:3], v93
	ds_read_b128 v[4:7], v95 offset:17408
	ds_read_b128 v[8:11], v94
	ds_read_b128 v[12:15], v93 offset:64
	ds_read_b128 v[16:19], v95 offset:17472
	s_waitcnt lgkmcnt(3)
	v_mfma_f32_16x16x32_bf16 v[0:3], v[0:3], v[4:7], 0
	ds_read_b128 v[4:7], v95 offset:52224
	ds_read_b128 v[20:23], v94 offset:64
	ds_read_b128 v[24:27], v95 offset:52288
	s_waitcnt lgkmcnt(2)
	v_mfma_f32_16x16x32_bf16 v[4:7], v[8:11], v[4:7], 0
	v_mfma_f32_16x16x32_bf16 v[0:3], v[12:15], v[16:19], v[0:3]
	ds_read_b128 v[8:11], v93 offset:128
	ds_read_b128 v[12:15], v95 offset:17536
	s_waitcnt lgkmcnt(2)
	v_mfma_f32_16x16x32_bf16 v[4:7], v[20:23], v[24:27], v[4:7]
	ds_read_b128 v[16:19], v94 offset:128
	ds_read_b128 v[20:23], v93 offset:192
	ds_read_b128 v[24:27], v95 offset:17600
	s_waitcnt lgkmcnt(3)
	v_mfma_f32_16x16x32_bf16 v[0:3], v[8:11], v[12:15], v[0:3]
	ds_read_b128 v[8:11], v95 offset:52352
	ds_read_b128 v[12:15], v94 offset:192
	ds_read_b128 v[54:57], v95 offset:52416
	s_waitcnt lgkmcnt(2)
	v_mfma_f32_16x16x32_bf16 v[4:7], v[16:19], v[8:11], v[4:7]
	v_mfma_f32_16x16x32_bf16 v[0:3], v[20:23], v[24:27], v[0:3]
	s_waitcnt lgkmcnt(0)
	v_mfma_f32_16x16x32_bf16 v[4:7], v[12:15], v[54:57], v[4:7]
	s_nop 5
	v_cndmask_b32_e64 v0, v0, 0, s[12:13]
	s_nop 0
	v_cndmask_b32_e64 v4, v4, 0, s[14:15]
	v_add_f32_e32 v0, v0, v4
	v_cvt_pk_bf16_f32 v0, v0, s0
	ds_write_b16 v105, v0 offset:18432
	v_cndmask_b32_e64 v0, v1, 0, s[16:17]
	v_cndmask_b32_e64 v1, 0, v5, s[12:13]
	v_add_f32_e32 v0, v0, v1
	v_cvt_pk_bf16_f32 v0, v0, s0
	ds_write_b16 v105, v0 offset:18576
	v_cndmask_b32_e64 v0, v2, 0, s[18:19]
	v_cndmask_b32_e64 v1, v6, 0, s[20:21]
	v_add_f32_e32 v0, v0, v1
	v_cvt_pk_bf16_f32 v0, v0, s0
	ds_write_b16 v105, v0 offset:18720
	v_cndmask_b32_e64 v0, v3, 0, s[22:23]
	v_cndmask_b32_e64 v1, v7, 0, s[24:25]
	v_add_f32_e32 v0, v0, v1
	v_cvt_pk_bf16_f32 v0, v0, s0
	ds_write_b16 v105, v0 offset:18864
	ds_read_b128 v[0:3], v93
	ds_read_b128 v[4:7], v96 offset:17408
	ds_read_b128 v[8:11], v94
	ds_read_b128 v[12:15], v93 offset:64
	ds_read_b128 v[16:19], v96 offset:17472
	s_waitcnt lgkmcnt(3)
	v_mfma_f32_16x16x32_bf16 v[0:3], v[0:3], v[4:7], 0
	ds_read_b128 v[4:7], v96 offset:52224
	ds_read_b128 v[20:23], v94 offset:64
	ds_read_b128 v[24:27], v96 offset:52288
	s_waitcnt lgkmcnt(2)
	v_mfma_f32_16x16x32_bf16 v[4:7], v[8:11], v[4:7], 0
	v_mfma_f32_16x16x32_bf16 v[0:3], v[12:15], v[16:19], v[0:3]
	ds_read_b128 v[8:11], v93 offset:128
	ds_read_b128 v[12:15], v96 offset:17536
	s_waitcnt lgkmcnt(2)
	v_mfma_f32_16x16x32_bf16 v[4:7], v[20:23], v[24:27], v[4:7]
	ds_read_b128 v[16:19], v94 offset:128
	ds_read_b128 v[20:23], v93 offset:192
	ds_read_b128 v[24:27], v96 offset:17600
	s_waitcnt lgkmcnt(3)
	v_mfma_f32_16x16x32_bf16 v[0:3], v[8:11], v[12:15], v[0:3]
	ds_read_b128 v[8:11], v96 offset:52352
	ds_read_b128 v[12:15], v94 offset:192
	ds_read_b128 v[54:57], v96 offset:52416
	s_waitcnt lgkmcnt(2)
	v_mfma_f32_16x16x32_bf16 v[4:7], v[16:19], v[8:11], v[4:7]
	v_mfma_f32_16x16x32_bf16 v[0:3], v[20:23], v[24:27], v[0:3]
	s_waitcnt lgkmcnt(0)
	v_mfma_f32_16x16x32_bf16 v[4:7], v[12:15], v[54:57], v[4:7]
	s_nop 5
	v_cndmask_b32_e64 v0, v0, 0, s[26:27]
	s_nop 0
	v_cndmask_b32_e64 v4, v4, 0, s[28:29]
	v_add_f32_e32 v0, v0, v4
	v_cvt_pk_bf16_f32 v0, v0, s0
	ds_write_b16 v105, v0 offset:18464
	v_cndmask_b32_e64 v0, v1, 0, s[30:31]
	v_cndmask_b32_e64 v1, 0, v5, s[26:27]
	v_add_f32_e32 v0, v0, v1
	v_cvt_pk_bf16_f32 v0, v0, s0
	ds_write_b16 v105, v0 offset:18608
	v_cndmask_b32_e64 v0, v2, 0, s[34:35]
	v_cndmask_b32_e64 v1, v6, 0, s[36:37]
	v_add_f32_e32 v0, v0, v1
	v_cvt_pk_bf16_f32 v0, v0, s0
	ds_write_b16 v105, v0 offset:18752
	v_cndmask_b32_e64 v0, v3, 0, s[38:39]
	v_cndmask_b32_e64 v1, v7, 0, s[40:41]
	v_add_f32_e32 v0, v0, v1
	v_cvt_pk_bf16_f32 v0, v0, s0
	s_lshl_b32 s0, s85, 3
	s_or_b32 s0, s1, s0
	s_ashr_i32 s1, s0, 31
	s_lshl_b64 s[46:47], s[0:1], 21
	s_or_b32 s0, s0, 1
	s_ashr_i32 s1, s0, 31
	s_lshl_b64 s[0:1], s[0:1], 21
	s_add_u32 s48, s52, s0
	s_addc_u32 s49, s53, s1
	s_add_u32 s0, s52, s46
	s_addc_u32 s1, s53, s47
	s_add_u32 s0, s0, s45
	s_addc_u32 s1, s1, 0
	v_lshl_add_u64 v[28:29], s[0:1], 0, v[30:31]
	v_lshl_add_u64 v[24:25], v[28:29], 0, v[36:37]
	ds_write_b16 v105, v0 offset:18896
	s_waitcnt lgkmcnt(0)
	s_barrier
	global_load_dwordx4 v[0:3], v[24:25], off
	global_load_dwordx4 v[4:7], v[24:25], off offset:64
	global_load_dwordx4 v[8:11], v[24:25], off offset:128
	ds_read_b128 v[12:15], v107
	ds_read_b128 v[16:19], v106 offset:18432
	ds_read_b128 v[20:23], v106 offset:18496
	ds_read_b128 v[54:57], v107 offset:64
	s_add_u32 s0, s48, s45
	global_load_dwordx4 v[24:27], v[24:25], off offset:192
	s_waitcnt lgkmcnt(2)
	v_mfma_f32_16x16x32_bf16 v[12:15], v[12:15], v[16:19], 0
	s_addc_u32 s1, s49, 0
	v_lshl_add_u64 v[82:83], s[0:1], 0, v[30:31]
	v_lshl_add_u64 v[74:75], v[82:83], 0, v[36:37]
	global_load_dwordx4 v[58:61], v[74:75], off
	s_waitcnt lgkmcnt(0)
	v_mfma_f32_16x16x32_bf16 v[12:15], v[54:57], v[20:23], v[12:15]
	ds_read_b128 v[54:57], v98
	ds_read_b128 v[62:65], v98 offset:64
	ds_read_b128 v[66:69], v98 offset:128
	ds_read_b128 v[70:73], v98 offset:192
	s_waitcnt vmcnt(4) lgkmcnt(3)
	v_mfma_f32_16x16x32_bf16 v[0:3], v[0:3], v[54:57], v[12:15]
	s_nop 2
	global_load_dwordx4 v[12:15], v[74:75], off offset:64
	v_lshl_add_u64 v[122:123], v[28:29], 0, v[38:39]
	v_lshl_add_u64 v[126:127], v[28:29], 0, v[40:41]
	s_waitcnt vmcnt(4) lgkmcnt(2)
	v_mfma_f32_16x16x32_bf16 v[0:3], v[4:7], v[62:65], v[0:3]
	global_load_dwordx4 v[4:7], v[74:75], off offset:128
	v_lshl_add_u64 v[28:29], v[28:29], 0, v[42:43]
	s_waitcnt vmcnt(4) lgkmcnt(1)
	v_mfma_f32_16x16x32_bf16 v[0:3], v[8:11], v[66:69], v[0:3]
	global_load_dwordx4 v[8:11], v[74:75], off offset:192
	s_nop 0
	global_load_dwordx4 v[74:77], v[122:123], off
	s_waitcnt vmcnt(5) lgkmcnt(0)
	v_mfma_f32_16x16x32_bf16 v[0:3], v[24:27], v[70:73], v[0:3]
	ds_read_b128 v[24:27], v98 offset:34816
	ds_read_b128 v[78:81], v98 offset:34880
	s_waitcnt vmcnt(4) lgkmcnt(1)
	v_mfma_f32_16x16x32_bf16 v[0:3], v[58:61], v[24:27], v[0:3]
	global_load_dwordx4 v[58:61], v[122:123], off offset:64
	ds_read_b128 v[114:117], v98 offset:34944
	ds_read_b128 v[118:121], v98 offset:35008
	global_load_dwordx4 v[130:133], v[28:29], off offset:192
	s_waitcnt vmcnt(5) lgkmcnt(2)
	v_mfma_f32_16x16x32_bf16 v[0:3], v[12:15], v[78:81], v[0:3]
	s_waitcnt vmcnt(4) lgkmcnt(1)
	v_mfma_f32_16x16x32_bf16 v[0:3], v[4:7], v[114:117], v[0:3]
	ds_read_b128 v[4:7], v107 offset:2304
	s_waitcnt vmcnt(3) lgkmcnt(1)
	v_mfma_f32_16x16x32_bf16 v[12:15], v[8:11], v[118:121], v[0:3]
	global_load_dwordx4 v[8:11], v[122:123], off offset:128
	s_nop 3
	ds_read_b128 v[0:3], v107 offset:2368
	s_waitcnt lgkmcnt(1)
	v_mfma_f32_16x16x32_bf16 v[4:7], v[4:7], v[16:19], 0
	s_waitcnt lgkmcnt(0)
	v_mfma_f32_16x16x32_bf16 v[0:3], v[0:3], v[20:23], v[4:7]
	s_nop 5
	global_load_dwordx4 v[4:7], v[122:123], off offset:192
	v_lshl_add_u64 v[122:123], v[82:83], 0, v[38:39]
	s_waitcnt vmcnt(4)
	v_mfma_f32_16x16x32_bf16 v[0:3], v[74:77], v[54:57], v[0:3]
	global_load_dwordx4 v[74:77], v[122:123], off
	s_waitcnt vmcnt(4)
	v_mfma_f32_16x16x32_bf16 v[0:3], v[58:61], v[62:65], v[0:3]
	global_load_dwordx4 v[58:61], v[122:123], off offset:64
	s_waitcnt vmcnt(3)
	v_mfma_f32_16x16x32_bf16 v[0:3], v[8:11], v[66:69], v[0:3]
	global_load_dwordx4 v[8:11], v[122:123], off offset:128
	s_waitcnt vmcnt(3)
	v_mfma_f32_16x16x32_bf16 v[0:3], v[4:7], v[70:73], v[0:3]
	global_load_dwordx4 v[4:7], v[122:123], off offset:192
	ds_read_b128 v[122:125], v107 offset:4608
	s_waitcnt vmcnt(3)
	v_mfma_f32_16x16x32_bf16 v[0:3], v[74:77], v[24:27], v[0:3]
	global_load_dwordx4 v[74:77], v[126:127], off
	s_waitcnt vmcnt(3)
	v_mfma_f32_16x16x32_bf16 v[0:3], v[58:61], v[78:81], v[0:3]
	global_load_dwordx4 v[58:61], v[126:127], off offset:64
	s_waitcnt vmcnt(3)
	v_mfma_f32_16x16x32_bf16 v[0:3], v[8:11], v[114:117], v[0:3]
	s_waitcnt vmcnt(2)
	v_mfma_f32_16x16x32_bf16 v[8:11], v[4:7], v[118:121], v[0:3]
	s_nop 5
	ds_read_b128 v[0:3], v107 offset:4672
	s_nop 0
	v_mul_f32_e32 v49, v11, v11
	s_waitcnt lgkmcnt(1)
	v_mfma_f32_16x16x32_bf16 v[4:7], v[122:125], v[16:19], 0
	global_load_dwordx4 v[122:125], v[126:127], off offset:128
	v_fmac_f32_e32 v49, v10, v10
	s_waitcnt lgkmcnt(0)
	v_mfma_f32_16x16x32_bf16 v[0:3], v[0:3], v[20:23], v[4:7]
	s_nop 3
	global_load_dwordx4 v[4:7], v[126:127], off offset:192
	v_lshl_add_u64 v[126:127], v[82:83], 0, v[40:41]
	s_waitcnt vmcnt(3)
	v_mfma_f32_16x16x32_bf16 v[0:3], v[74:77], v[54:57], v[0:3]
	global_load_dwordx4 v[74:77], v[126:127], off
	s_waitcnt vmcnt(3)
	v_mfma_f32_16x16x32_bf16 v[0:3], v[58:61], v[62:65], v[0:3]
	global_load_dwordx4 v[58:61], v[126:127], off offset:64
	s_waitcnt vmcnt(3)
	v_mfma_f32_16x16x32_bf16 v[0:3], v[122:125], v[66:69], v[0:3]
	global_load_dwordx4 v[122:125], v[126:127], off offset:128
	s_waitcnt vmcnt(3)
	v_mfma_f32_16x16x32_bf16 v[0:3], v[4:7], v[70:73], v[0:3]
	global_load_dwordx4 v[4:7], v[126:127], off offset:192
	s_nop 0
	global_load_dwordx4 v[126:129], v[28:29], off offset:128
	s_waitcnt vmcnt(4)
	v_mfma_f32_16x16x32_bf16 v[0:3], v[74:77], v[24:27], v[0:3]
	global_load_dwordx4 v[74:77], v[28:29], off
	s_waitcnt vmcnt(4)
	v_mfma_f32_16x16x32_bf16 v[0:3], v[58:61], v[78:81], v[0:3]
	global_load_dwordx4 v[58:61], v[28:29], off offset:64
	v_lshl_add_u64 v[28:29], v[82:83], 0, v[42:43]
	s_waitcnt vmcnt(4)
	v_mfma_f32_16x16x32_bf16 v[0:3], v[122:125], v[114:117], v[0:3]
	ds_read_b128 v[122:125], v108
	s_waitcnt vmcnt(3)
	v_mfma_f32_16x16x32_bf16 v[4:7], v[4:7], v[118:121], v[0:3]
	s_nop 4
	ds_read_b128 v[0:3], v108 offset:64
	s_waitcnt lgkmcnt(1)
	v_mfma_f32_16x16x32_bf16 v[16:19], v[122:125], v[16:19], 0
	global_load_dwordx4 v[122:125], v[28:29], off
	s_waitcnt lgkmcnt(0)
	v_mfma_f32_16x16x32_bf16 v[0:3], v[0:3], v[20:23], v[16:19]
	global_load_dwordx4 v[20:23], v[28:29], off offset:128
	s_nop 3
	global_load_dwordx4 v[16:19], v[28:29], off offset:64
	s_waitcnt vmcnt(4)
	v_mfma_f32_16x16x32_bf16 v[0:3], v[74:77], v[54:57], v[0:3]
	global_load_dwordx4 v[54:57], v[28:29], off offset:192
	v_mul_f32_e32 v28, v13, v13
	v_mul_f32_e32 v29, v15, v15
	s_waitcnt vmcnt(4)
	v_mfma_f32_16x16x32_bf16 v[0:3], v[58:61], v[62:65], v[0:3]
	v_fmac_f32_e32 v28, v12, v12
	v_fmac_f32_e32 v29, v14, v14
	v_add_f32_e32 v28, v28, v29
	v_mfma_f32_16x16x32_bf16 v[0:3], v[126:129], v[66:69], v[0:3]
	v_mul_f32_e32 v29, v9, v9
	v_fmac_f32_e32 v29, v8, v8
	v_mfma_f32_16x16x32_bf16 v[0:3], v[130:133], v[70:73], v[0:3]
	s_waitcnt vmcnt(3)
	v_mfma_f32_16x16x32_bf16 v[0:3], v[122:125], v[24:27], v[0:3]
	v_add_f32_e32 v24, v29, v49
	v_add_f32_e32 v24, v28, v24
	s_waitcnt vmcnt(1)
	v_mfma_f32_16x16x32_bf16 v[0:3], v[16:19], v[78:81], v[0:3]
	v_mul_f32_e32 v16, v5, v5
	v_mul_f32_e32 v17, v7, v7
	v_fmac_f32_e32 v16, v4, v4
	v_mfma_f32_16x16x32_bf16 v[0:3], v[20:23], v[114:117], v[0:3]
	v_fmac_f32_e32 v17, v6, v6
	v_add_f32_e32 v16, v16, v17
	v_add_f32_e32 v16, v24, v16
	s_waitcnt vmcnt(0)
	v_mfma_f32_16x16x32_bf16 v[0:3], v[54:57], v[118:121], v[0:3]
	s_nop 7
	v_mul_f32_e32 v17, v1, v1
	v_mul_f32_e32 v18, v3, v3
	v_fmac_f32_e32 v17, v0, v0
	v_fmac_f32_e32 v18, v2, v2
	v_add_f32_e32 v17, v17, v18
	v_add_f32_e32 v16, v16, v17
	ds_bpermute_b32 v17, v101, v16
	s_waitcnt lgkmcnt(0)
	v_add_f32_e32 v16, v16, v17
	ds_bpermute_b32 v17, v102, v16
	s_and_saveexec_b64 s[0:1], s[42:43]
	s_cbranch_execz .LBB0_819
	s_waitcnt lgkmcnt(0)
	v_add_f32_e32 v16, v16, v17
	ds_write_b32 v99, v16 offset:27648
	s_branch .LBB0_819
